# loop-counter and pointer SALU updates moved from after the last barrier into the last MFMA block in 5 GEMM loops
# baseline (speedup 1.0000x reference)
; #define PG8_STAGE(bufoff, gbase, voff) do { _Pragma("unroll") for (int _i = 0; _i < 2; ++_i) \
;         __builtin_amdgcn_global_load_lds((const unsigned*)((const char*)(gbase) + (voff)[_i]), (PG8_LAS unsigned*)(lds + (bufoff) + ldsw + _i * 8192), 16, 0, 0); } while (0)
; #define PG8_LDA(dst, b, h) do { _Pragma("unroll") for (int m = 0; m < 4; ++m) _Pragma("unroll") for (int k = 0; k < 2; ++k) dst[m][k] = *(const PG8_LAS bf16x8*)(lds + PG8_SA(b, h) + aoff + m * 2048 + k * 1024); } while (0)
; #define PG8_LDB(dst, b, h) do { _Pragma("unroll") for (int n = 0; n < 2; ++n) _Pragma("unroll") for (int k = 0; k < 2; ++k) dst[n][k] = *(const PG8_LAS bf16x8*)(lds + PG8_SB(b, h) + boff + n * 2048 + k * 1024); } while (0)
; #define PG8_MMA(ai, bj, At, Bt) do { __builtin_amdgcn_s_setprio(1); _Pragma("unroll") for (int m = 0; m < 4; ++m) _Pragma("unroll") for (int n = 0; n < 2; ++n) _Pragma("unroll") for (int k = 0; k < 2; ++k) \
;         acc[ai][bj][m][n] = __builtin_amdgcn_mfma_f32_16x16x32_bf16(Bt[n][k], At[m][k], acc[ai][bj][m][n], 0, 0, 0); __builtin_amdgcn_s_setprio(0); } while (0)
; #define PG8_WAIT_V(n) asm volatile("s_waitcnt vmcnt(" #n ")" ::: "memory")
; #define PG8_WAIT_L(n) asm volatile("s_waitcnt lgkmcnt(" #n ")" ::: "memory")
; template <class Epi, class Sched, bool ALIGN_EPI = false, bool SP2 = false, bool ABLK = false>
; __device__ __forceinline__ void gemm_phase(PG8_LAS unsigned char* lds, const Gemm g, const Sched& S, const Epi& E) {
;     ...
;             const bool last = (t == nt - 2);
;             const char* a1 = cA + (size_t)(t + 1) * kstepA;
;             const char* a2 = last ? nA : cA + (size_t)(t + 2) * kstepA; const char* b2 = last ? nB : cB + (size_t)(t + 2) * kstep;
;             const char* a3 = a2 + kstepA; const char* b3 = b2 + kstep;
;             if (last && has_next) S.a_ready(nxt);
;             if constexpr (SP2) {
;             PG8_LDB(B0, 0, 0); PG8_LDB(B1, 0, 1); PG8_SCHED; PG8_LDA(At, 0, 0); PG8_STAGE(PG8_SA(1, 1), a1 + hstepA, voffA);
;             PG8_WAIT_V(8); PG8_WAIT_L(0); PG8_BAR; PG8_MMA(0, 0, At, B0); PG8_MMA(0, 1, At, B1); PG8_BAR; PG8_SCHED;
;             PG8_LDA(At, 0, 1); PG8_STAGE(PG8_SB(0, 0), b2, voffB); PG8_STAGE(PG8_SB(0, 1), b2 + hstep, voffB); PG8_STAGE(PG8_SA(0, 0), a2, voffA);
;             PG8_WAIT_V(8); PG8_WAIT_L(0); PG8_BAR; PG8_MMA(1, 0, At, B0); PG8_MMA(1, 1, At, B1); PG8_BAR; PG8_SCHED;
.LBB0_175:
	ds_read_b128 v[162:165], v159
	ds_read_b128 v[168:171], v159 offset:1024
	ds_read_b128 v[172:175], v159 offset:2048
	ds_read_b128 v[176:179], v159 offset:3072
	ds_read_b128 v[180:183], v160
	ds_read_b128 v[184:187], v160 offset:1024
	ds_read_b128 v[188:191], v160 offset:2048
	ds_read_b128 v[192:195], v160 offset:3072
	s_add_u32 s26, s24, 0xfffc0080
	s_addc_u32 s27, s25, -1
	s_cmp_eq_u32 s51, 12
	s_cselect_b32 s29, s17, s27
	s_cselect_b32 s28, s47, s26
	s_cselect_b32 s27, s15, s50
	s_cselect_b32 s26, s48, s49
	v_lshl_add_u64 v[156:157], s[24:25], 0, v[148:149]
	s_add_i32 m0, s23, 0xc000
	ds_read_b128 v[196:199], v161
	ds_read_b128 v[200:203], v161 offset:1024
	ds_read_b128 v[204:207], v161 offset:2048
	ds_read_b128 v[208:211], v161 offset:3072
	ds_read_b128 v[212:215], v161 offset:4096
	ds_read_b128 v[216:219], v161 offset:5120
	ds_read_b128 v[220:223], v161 offset:6144
	ds_read_b128 v[224:227], v161 offset:7168
	global_load_lds_dwordx4 v[156:157], off
	v_lshl_add_u64 v[156:157], s[24:25], 0, v[150:151]
	s_add_i32 m0, s23, 0xe000
	s_nop 0
	global_load_lds_dwordx4 v[156:157], off
	s_waitcnt vmcnt(8)
	s_waitcnt lgkmcnt(0)
	s_barrier
	s_setprio 1
	s_waitcnt lgkmcnt(0)
	v_mfma_f32_16x16x32_bf16 v[124:127], v[162:165], v[196:199], v[124:127]
	v_mfma_f32_16x16x32_bf16 v[120:123], v[172:175], v[196:199], v[120:123]
	v_mfma_f32_16x16x32_bf16 v[108:111], v[162:165], v[204:207], v[108:111]
	v_mfma_f32_16x16x32_bf16 v[104:107], v[172:175], v[204:207], v[104:107]
	v_mfma_f32_16x16x32_bf16 v[92:95], v[162:165], v[212:215], v[92:95]
	v_mfma_f32_16x16x32_bf16 v[88:91], v[172:175], v[212:215], v[88:91]
	v_mfma_f32_16x16x32_bf16 v[76:79], v[162:165], v[220:223], v[76:79]
	v_mfma_f32_16x16x32_bf16 v[72:75], v[172:175], v[220:223], v[72:75]
	v_mfma_f32_16x16x32_bf16 v[124:127], v[168:171], v[200:203], v[124:127]
	v_mfma_f32_16x16x32_bf16 v[120:123], v[176:179], v[200:203], v[120:123]
	v_mfma_f32_16x16x32_bf16 v[108:111], v[168:171], v[208:211], v[108:111]
	v_mfma_f32_16x16x32_bf16 v[104:107], v[176:179], v[208:211], v[104:107]
	v_mfma_f32_16x16x32_bf16 v[92:95], v[168:171], v[216:219], v[92:95]
	v_mfma_f32_16x16x32_bf16 v[88:91], v[176:179], v[216:219], v[88:91]
	v_mfma_f32_16x16x32_bf16 v[76:79], v[168:171], v[224:227], v[76:79]
	v_mfma_f32_16x16x32_bf16 v[72:75], v[176:179], v[224:227], v[72:75]
	s_setprio 0
	s_setprio 1
	v_mfma_f32_16x16x32_bf16 v[116:119], v[180:183], v[196:199], v[116:119]
	v_mfma_f32_16x16x32_bf16 v[112:115], v[188:191], v[196:199], v[112:115]
	v_mfma_f32_16x16x32_bf16 v[100:103], v[180:183], v[204:207], v[100:103]
	v_mfma_f32_16x16x32_bf16 v[96:99], v[188:191], v[204:207], v[96:99]
	v_mfma_f32_16x16x32_bf16 v[84:87], v[180:183], v[212:215], v[84:87]
	v_mfma_f32_16x16x32_bf16 v[80:83], v[188:191], v[212:215], v[80:83]
	v_mfma_f32_16x16x32_bf16 v[68:71], v[180:183], v[220:223], v[68:71]
	v_mfma_f32_16x16x32_bf16 v[64:67], v[188:191], v[220:223], v[64:67]
	v_mfma_f32_16x16x32_bf16 v[116:119], v[184:187], v[200:203], v[116:119]
	v_mfma_f32_16x16x32_bf16 v[112:115], v[192:195], v[200:203], v[112:115]
	v_mfma_f32_16x16x32_bf16 v[100:103], v[184:187], v[208:211], v[100:103]
	v_mfma_f32_16x16x32_bf16 v[96:99], v[192:195], v[208:211], v[96:99]
	v_mfma_f32_16x16x32_bf16 v[84:87], v[184:187], v[216:219], v[84:87]
	v_mfma_f32_16x16x32_bf16 v[80:83], v[192:195], v[216:219], v[80:83]
	v_mfma_f32_16x16x32_bf16 v[68:71], v[184:187], v[224:227], v[68:71]
	v_mfma_f32_16x16x32_bf16 v[64:67], v[192:195], v[224:227], v[64:67]
	s_setprio 0
	s_barrier
	s_add_i32 s53, s43, s30
	v_lshl_add_u64 v[156:157], s[26:27], 0, v[132:133]
	s_mov_b32 m0, s53
	ds_read_b128 v[196:199], v161 offset:16384
	ds_read_b128 v[200:203], v161 offset:17408
	ds_read_b128 v[204:207], v161 offset:18432
	ds_read_b128 v[208:211], v161 offset:19456
	ds_read_b128 v[212:215], v161 offset:20480
	ds_read_b128 v[216:219], v161 offset:21504
	ds_read_b128 v[220:223], v161 offset:22528
	ds_read_b128 v[224:227], v161 offset:23552
	global_load_lds_dwordx4 v[156:157], off
	s_add_i32 m0, s53, 0x2000
	s_add_u32 s54, s26, 0x40000
	v_lshl_add_u64 v[228:229], s[26:27], 0, v[128:129]
	s_addc_u32 s55, s27, 0
	s_add_i32 s53, s44, s30
	global_load_lds_dwordx4 v[228:229], off
	v_lshl_add_u64 v[230:231], s[54:55], 0, v[132:133]
	s_mov_b32 m0, s53
	v_lshl_add_u64 v[232:233], s[28:29], 0, v[130:131]
	global_load_lds_dwordx4 v[230:231], off
	v_lshl_add_u64 v[230:231], s[54:55], 0, v[128:129]
	s_add_i32 m0, s53, 0x2000
	s_nop 0
	global_load_lds_dwordx4 v[230:231], off
	v_lshl_add_u64 v[230:231], s[28:29], 0, v[134:135]
	s_mov_b32 m0, s23
	s_nop 0
	global_load_lds_dwordx4 v[230:231], off
	s_mov_b32 m0, s34
	s_nop 0
	global_load_lds_dwordx4 v[232:233], off
	s_waitcnt vmcnt(8)
	s_waitcnt lgkmcnt(0)
	s_barrier
; #define PG8_STAGE(bufoff, gbase, voff) do { _Pragma("unroll") for (int _i = 0; _i < 2; ++_i) \
;         __builtin_amdgcn_global_load_lds((const unsigned*)((const char*)(gbase) + (voff)[_i]), (PG8_LAS unsigned*)(lds + (bufoff) + ldsw + _i * 8192), 16, 0, 0); } while (0)
; #define PG8_LDA(dst, b, h) do { _Pragma("unroll") for (int m = 0; m < 4; ++m) _Pragma("unroll") for (int k = 0; k < 2; ++k) dst[m][k] = *(const PG8_LAS bf16x8*)(lds + PG8_SA(b, h) + aoff + m * 2048 + k * 1024); } while (0)
; #define PG8_LDB(dst, b, h) do { _Pragma("unroll") for (int n = 0; n < 2; ++n) _Pragma("unroll") for (int k = 0; k < 2; ++k) dst[n][k] = *(const PG8_LAS bf16x8*)(lds + PG8_SB(b, h) + boff + n * 2048 + k * 1024); } while (0)
; #define PG8_MMA(ai, bj, At, Bt) do { __builtin_amdgcn_s_setprio(1); _Pragma("unroll") for (int m = 0; m < 4; ++m) _Pragma("unroll") for (int n = 0; n < 2; ++n) _Pragma("unroll") for (int k = 0; k < 2; ++k) \
;         acc[ai][bj][m][n] = __builtin_amdgcn_mfma_f32_16x16x32_bf16(Bt[n][k], At[m][k], acc[ai][bj][m][n], 0, 0, 0); __builtin_amdgcn_s_setprio(0); } while (0)
; #define PG8_WAIT_V(n) asm volatile("s_waitcnt vmcnt(" #n ")" ::: "memory")
; #define PG8_WAIT_L(n) asm volatile("s_waitcnt lgkmcnt(" #n ")" ::: "memory")
; #define PG8_BAR __builtin_amdgcn_s_barrier()
; #define PG8_SCHED __builtin_amdgcn_sched_barrier(0)
; template <class Epi, class Sched, bool ALIGN_EPI = false, bool SP2 = false, bool ABLK = false>
; __device__ __forceinline__ void gemm_phase(PG8_LAS unsigned char* lds, const Gemm g, const Sched& S, const Epi& E) {
;     ...
;             PG8_WAIT_V(8); PG8_WAIT_L(0); PG8_BAR; PG8_MMA(1, 0, At, B0); PG8_MMA(1, 1, At, B1); PG8_BAR; PG8_SCHED;
;             PG8_LDB(B0, 1, 0); PG8_LDB(B1, 1, 1); PG8_SCHED; PG8_LDA(At, 1, 0); PG8_STAGE(PG8_SA(0, 1), a2 + hstepA, voffA);
;             PG8_WAIT_V(8); PG8_WAIT_L(0); PG8_BAR; PG8_MMA(0, 0, At, B0); PG8_MMA(0, 1, At, B1); PG8_BAR; PG8_SCHED;
;             PG8_LDA(At, 1, 1); PG8_STAGE(PG8_SB(1, 0), b3, voffB); PG8_STAGE(PG8_SB(1, 1), b3 + hstep, voffB); PG8_STAGE(PG8_SA(1, 0), a3, voffA);
	s_setprio 1
	s_waitcnt lgkmcnt(0)
	v_mfma_f32_16x16x32_bf16 v[60:63], v[162:165], v[196:199], v[60:63]
	v_mfma_f32_16x16x32_bf16 v[56:59], v[172:175], v[196:199], v[56:59]
	v_mfma_f32_16x16x32_bf16 v[44:47], v[162:165], v[204:207], v[44:47]
	v_mfma_f32_16x16x32_bf16 v[40:43], v[172:175], v[204:207], v[40:43]
	v_mfma_f32_16x16x32_bf16 v[28:31], v[162:165], v[212:215], v[28:31]
	v_mfma_f32_16x16x32_bf16 v[24:27], v[172:175], v[212:215], v[24:27]
	v_mfma_f32_16x16x32_bf16 v[12:15], v[162:165], v[220:223], v[12:15]
	v_mfma_f32_16x16x32_bf16 v[8:11], v[172:175], v[220:223], v[8:11]
	v_mfma_f32_16x16x32_bf16 v[60:63], v[168:171], v[200:203], v[60:63]
	v_mfma_f32_16x16x32_bf16 v[56:59], v[176:179], v[200:203], v[56:59]
	v_mfma_f32_16x16x32_bf16 v[44:47], v[168:171], v[208:211], v[44:47]
	v_mfma_f32_16x16x32_bf16 v[40:43], v[176:179], v[208:211], v[40:43]
	v_mfma_f32_16x16x32_bf16 v[28:31], v[168:171], v[216:219], v[28:31]
	v_mfma_f32_16x16x32_bf16 v[24:27], v[176:179], v[216:219], v[24:27]
	v_mfma_f32_16x16x32_bf16 v[12:15], v[168:171], v[224:227], v[12:15]
	v_mfma_f32_16x16x32_bf16 v[8:11], v[176:179], v[224:227], v[8:11]
	s_setprio 0
	s_setprio 1
	v_mfma_f32_16x16x32_bf16 v[52:55], v[180:183], v[196:199], v[52:55]
	v_mfma_f32_16x16x32_bf16 v[48:51], v[188:191], v[196:199], v[48:51]
	v_mfma_f32_16x16x32_bf16 v[36:39], v[180:183], v[204:207], v[36:39]
	v_mfma_f32_16x16x32_bf16 v[32:35], v[188:191], v[204:207], v[32:35]
	v_mfma_f32_16x16x32_bf16 v[20:23], v[180:183], v[212:215], v[20:23]
	v_mfma_f32_16x16x32_bf16 v[16:19], v[188:191], v[212:215], v[16:19]
	v_mfma_f32_16x16x32_bf16 v[4:7], v[180:183], v[220:223], v[4:7]
	v_mfma_f32_16x16x32_bf16 v[0:3], v[188:191], v[220:223], v[0:3]
	v_mfma_f32_16x16x32_bf16 v[52:55], v[184:187], v[200:203], v[52:55]
	v_mfma_f32_16x16x32_bf16 v[48:51], v[192:195], v[200:203], v[48:51]
	v_mfma_f32_16x16x32_bf16 v[36:39], v[184:187], v[208:211], v[36:39]
	v_mfma_f32_16x16x32_bf16 v[32:35], v[192:195], v[208:211], v[32:35]
	v_mfma_f32_16x16x32_bf16 v[20:23], v[184:187], v[216:219], v[20:23]
	v_mfma_f32_16x16x32_bf16 v[16:19], v[192:195], v[216:219], v[16:19]
	v_mfma_f32_16x16x32_bf16 v[4:7], v[184:187], v[224:227], v[4:7]
	v_mfma_f32_16x16x32_bf16 v[0:3], v[192:195], v[224:227], v[0:3]
	s_setprio 0
	s_barrier
	s_add_i32 s53, 0, 0x18000
	v_add_u32_e32 v167, s53, v158
	s_add_i32 s54, 0, 0x1c000
	ds_read_b128 v[162:165], v167
	ds_read_b128 v[168:171], v167 offset:1024
	ds_read_b128 v[172:175], v167 offset:2048
	ds_read_b128 v[176:179], v167 offset:3072
	v_add_u32_e32 v167, s54, v158
	ds_read_b128 v[180:183], v167
	ds_read_b128 v[184:187], v167 offset:1024
	ds_read_b128 v[188:191], v167 offset:2048
	ds_read_b128 v[192:195], v167 offset:3072
	s_add_u32 s28, s28, 0x40000
	s_addc_u32 s29, s29, 0
	s_mov_b32 m0, s35
	v_lshl_add_u64 v[234:235], s[28:29], 0, v[134:135]
	ds_read_b128 v[196:199], v161 offset:32768
	ds_read_b128 v[200:203], v161 offset:33792
	ds_read_b128 v[204:207], v161 offset:34816
	ds_read_b128 v[208:211], v161 offset:35840
	ds_read_b128 v[212:215], v161 offset:36864
	ds_read_b128 v[216:219], v161 offset:37888
	ds_read_b128 v[220:223], v161 offset:38912
	ds_read_b128 v[224:227], v161 offset:39936
	global_load_lds_dwordx4 v[234:235], off
	v_lshl_add_u64 v[234:235], s[28:29], 0, v[130:131]
	s_mov_b32 m0, s38
	s_nop 0
	global_load_lds_dwordx4 v[234:235], off
	s_waitcnt vmcnt(8)
	s_waitcnt lgkmcnt(0)
	s_barrier
	s_setprio 1
	s_waitcnt lgkmcnt(0)
	v_mfma_f32_16x16x32_bf16 v[124:127], v[162:165], v[196:199], v[124:127]
	v_mfma_f32_16x16x32_bf16 v[120:123], v[172:175], v[196:199], v[120:123]
	v_mfma_f32_16x16x32_bf16 v[108:111], v[162:165], v[204:207], v[108:111]
	v_mfma_f32_16x16x32_bf16 v[104:107], v[172:175], v[204:207], v[104:107]
	v_mfma_f32_16x16x32_bf16 v[92:95], v[162:165], v[212:215], v[92:95]
	v_mfma_f32_16x16x32_bf16 v[88:91], v[172:175], v[212:215], v[88:91]
	v_mfma_f32_16x16x32_bf16 v[76:79], v[162:165], v[220:223], v[76:79]
	v_mfma_f32_16x16x32_bf16 v[72:75], v[172:175], v[220:223], v[72:75]
	v_mfma_f32_16x16x32_bf16 v[124:127], v[168:171], v[200:203], v[124:127]
	v_mfma_f32_16x16x32_bf16 v[120:123], v[176:179], v[200:203], v[120:123]
	v_mfma_f32_16x16x32_bf16 v[108:111], v[168:171], v[208:211], v[108:111]
	v_mfma_f32_16x16x32_bf16 v[104:107], v[176:179], v[208:211], v[104:107]
	v_mfma_f32_16x16x32_bf16 v[92:95], v[168:171], v[216:219], v[92:95]
	v_mfma_f32_16x16x32_bf16 v[88:91], v[176:179], v[216:219], v[88:91]
	v_mfma_f32_16x16x32_bf16 v[76:79], v[168:171], v[224:227], v[76:79]
	v_mfma_f32_16x16x32_bf16 v[72:75], v[176:179], v[224:227], v[72:75]
	s_setprio 0
	s_setprio 1
	v_mfma_f32_16x16x32_bf16 v[116:119], v[180:183], v[196:199], v[116:119]
	v_mfma_f32_16x16x32_bf16 v[112:115], v[188:191], v[196:199], v[112:115]
	v_mfma_f32_16x16x32_bf16 v[100:103], v[180:183], v[204:207], v[100:103]
	v_mfma_f32_16x16x32_bf16 v[96:99], v[188:191], v[204:207], v[96:99]
	v_mfma_f32_16x16x32_bf16 v[84:87], v[180:183], v[212:215], v[84:87]
	v_mfma_f32_16x16x32_bf16 v[80:83], v[188:191], v[212:215], v[80:83]
	v_mfma_f32_16x16x32_bf16 v[68:71], v[180:183], v[220:223], v[68:71]
	v_mfma_f32_16x16x32_bf16 v[64:67], v[188:191], v[220:223], v[64:67]
	v_mfma_f32_16x16x32_bf16 v[116:119], v[184:187], v[200:203], v[116:119]
	v_mfma_f32_16x16x32_bf16 v[112:115], v[192:195], v[200:203], v[112:115]
	v_mfma_f32_16x16x32_bf16 v[100:103], v[184:187], v[208:211], v[100:103]
	v_mfma_f32_16x16x32_bf16 v[96:99], v[192:195], v[208:211], v[96:99]
	v_mfma_f32_16x16x32_bf16 v[84:87], v[184:187], v[216:219], v[84:87]
	v_mfma_f32_16x16x32_bf16 v[80:83], v[192:195], v[216:219], v[80:83]
	v_mfma_f32_16x16x32_bf16 v[68:71], v[184:187], v[224:227], v[68:71]
	v_mfma_f32_16x16x32_bf16 v[64:67], v[192:195], v[224:227], v[64:67]
	s_setprio 0
	s_barrier
; #define PG8_STAGE(bufoff, gbase, voff) do { _Pragma("unroll") for (int _i = 0; _i < 2; ++_i) \
;         __builtin_amdgcn_global_load_lds((const unsigned*)((const char*)(gbase) + (voff)[_i]), (PG8_LAS unsigned*)(lds + (bufoff) + ldsw + _i * 8192), 16, 0, 0); } while (0)
; #define PG8_LDA(dst, b, h) do { _Pragma("unroll") for (int m = 0; m < 4; ++m) _Pragma("unroll") for (int k = 0; k < 2; ++k) dst[m][k] = *(const PG8_LAS bf16x8*)(lds + PG8_SA(b, h) + aoff + m * 2048 + k * 1024); } while (0)
; #define PG8_MMA(ai, bj, At, Bt) do { __builtin_amdgcn_s_setprio(1); _Pragma("unroll") for (int m = 0; m < 4; ++m) _Pragma("unroll") for (int n = 0; n < 2; ++n) _Pragma("unroll") for (int k = 0; k < 2; ++k) \
;         acc[ai][bj][m][n] = __builtin_amdgcn_mfma_f32_16x16x32_bf16(Bt[n][k], At[m][k], acc[ai][bj][m][n], 0, 0, 0); __builtin_amdgcn_s_setprio(0); } while (0)
; #define PG8_WAIT_V(n) asm volatile("s_waitcnt vmcnt(" #n ")" ::: "memory")
; #define PG8_WAIT_L(n) asm volatile("s_waitcnt lgkmcnt(" #n ")" ::: "memory")
; #define PG8_BAR __builtin_amdgcn_s_barrier()
; #define PG8_SCHED __builtin_amdgcn_sched_barrier(0)
; template <class Epi, class Sched, bool ALIGN_EPI = false, bool SP2 = false, bool ABLK = false>
; __device__ __forceinline__ void gemm_phase(PG8_LAS unsigned char* lds, const Gemm g, const Sched& S, const Epi& E) {
;     ...
;         for (int t = 0; t < nt; t += 2) {
;     ...
;             PG8_LDA(At, 1, 1); PG8_STAGE(PG8_SB(1, 0), b3, voffB); PG8_STAGE(PG8_SB(1, 1), b3 + hstep, voffB); PG8_STAGE(PG8_SA(1, 0), a3, voffA);
;             PG8_WAIT_V(8); PG8_WAIT_L(0); PG8_BAR; PG8_MMA(1, 0, At, B0); PG8_MMA(1, 1, At, B1); PG8_BAR; PG8_SCHED;
	s_add_i32 s28, s53, s30
	v_lshl_add_u64 v[156:157], v[156:157], 0, s[8:9]
	s_mov_b32 m0, s28
	ds_read_b128 v[196:199], v161 offset:49152
	ds_read_b128 v[200:203], v161 offset:50176
	ds_read_b128 v[204:207], v161 offset:51200
	ds_read_b128 v[208:211], v161 offset:52224
	ds_read_b128 v[212:215], v161 offset:53248
	ds_read_b128 v[216:219], v161 offset:54272
	ds_read_b128 v[220:223], v161 offset:55296
	ds_read_b128 v[224:227], v161 offset:56320
	global_load_lds_dwordx4 v[156:157], off
	s_add_i32 m0, s28, 0x2000
	s_add_u32 s26, s26, 0x40080
	v_lshl_add_u64 v[156:157], v[228:229], 0, s[8:9]
	s_addc_u32 s27, s27, 0
	s_add_i32 s28, s54, s30
	global_load_lds_dwordx4 v[156:157], off
	v_lshl_add_u64 v[156:157], s[26:27], 0, v[132:133]
	s_mov_b32 m0, s28
	s_nop 0
	global_load_lds_dwordx4 v[156:157], off
	v_lshl_add_u64 v[156:157], s[26:27], 0, v[128:129]
	s_add_i32 m0, s28, 0x2000
	s_nop 0
	global_load_lds_dwordx4 v[156:157], off
	v_lshl_add_u64 v[156:157], v[230:231], 0, s[8:9]
	s_mov_b32 m0, s41
	s_nop 0
	global_load_lds_dwordx4 v[156:157], off
	v_lshl_add_u64 v[156:157], v[232:233], 0, s[8:9]
	s_mov_b32 m0, s42
	s_nop 0
	global_load_lds_dwordx4 v[156:157], off
	s_waitcnt vmcnt(8)
	s_waitcnt lgkmcnt(0)
	s_barrier
	s_setprio 1
	s_waitcnt lgkmcnt(0)
	v_mfma_f32_16x16x32_bf16 v[60:63], v[162:165], v[196:199], v[60:63]
	v_mfma_f32_16x16x32_bf16 v[56:59], v[172:175], v[196:199], v[56:59]
	v_mfma_f32_16x16x32_bf16 v[44:47], v[162:165], v[204:207], v[44:47]
	v_mfma_f32_16x16x32_bf16 v[40:43], v[172:175], v[204:207], v[40:43]
	v_mfma_f32_16x16x32_bf16 v[28:31], v[162:165], v[212:215], v[28:31]
	v_mfma_f32_16x16x32_bf16 v[24:27], v[172:175], v[212:215], v[24:27]
	v_mfma_f32_16x16x32_bf16 v[12:15], v[162:165], v[220:223], v[12:15]
	v_mfma_f32_16x16x32_bf16 v[8:11], v[172:175], v[220:223], v[8:11]
	v_mfma_f32_16x16x32_bf16 v[60:63], v[168:171], v[200:203], v[60:63]
	v_mfma_f32_16x16x32_bf16 v[56:59], v[176:179], v[200:203], v[56:59]
	v_mfma_f32_16x16x32_bf16 v[44:47], v[168:171], v[208:211], v[44:47]
	v_mfma_f32_16x16x32_bf16 v[40:43], v[176:179], v[208:211], v[40:43]
	v_mfma_f32_16x16x32_bf16 v[28:31], v[168:171], v[216:219], v[28:31]
	v_mfma_f32_16x16x32_bf16 v[24:27], v[176:179], v[216:219], v[24:27]
	v_mfma_f32_16x16x32_bf16 v[12:15], v[168:171], v[224:227], v[12:15]
	v_mfma_f32_16x16x32_bf16 v[8:11], v[176:179], v[224:227], v[8:11]
	s_setprio 0
	s_setprio 1
	v_mfma_f32_16x16x32_bf16 v[52:55], v[180:183], v[196:199], v[52:55]
	v_mfma_f32_16x16x32_bf16 v[48:51], v[188:191], v[196:199], v[48:51]
	v_mfma_f32_16x16x32_bf16 v[36:39], v[180:183], v[204:207], v[36:39]
	v_mfma_f32_16x16x32_bf16 v[32:35], v[188:191], v[204:207], v[32:35]
	v_mfma_f32_16x16x32_bf16 v[20:23], v[180:183], v[212:215], v[20:23]
	v_mfma_f32_16x16x32_bf16 v[16:19], v[188:191], v[212:215], v[16:19]
	v_mfma_f32_16x16x32_bf16 v[4:7], v[180:183], v[220:223], v[4:7]
	v_mfma_f32_16x16x32_bf16 v[0:3], v[188:191], v[220:223], v[0:3]
	v_mfma_f32_16x16x32_bf16 v[52:55], v[184:187], v[200:203], v[52:55]
	v_mfma_f32_16x16x32_bf16 v[48:51], v[192:195], v[200:203], v[48:51]
	v_mfma_f32_16x16x32_bf16 v[36:39], v[184:187], v[208:211], v[36:39]
	v_mfma_f32_16x16x32_bf16 v[32:35], v[192:195], v[208:211], v[32:35]
	v_mfma_f32_16x16x32_bf16 v[20:23], v[184:187], v[216:219], v[20:23]
	v_mfma_f32_16x16x32_bf16 v[16:19], v[192:195], v[216:219], v[16:19]
	v_mfma_f32_16x16x32_bf16 v[4:7], v[184:187], v[224:227], v[4:7]
	v_mfma_f32_16x16x32_bf16 v[0:3], v[192:195], v[224:227], v[0:3]
	s_add_i32 s51, s51, 2
	s_add_u32 s24, s24, 0x100
	s_addc_u32 s25, s25, 0
	s_add_u32 s49, s49, 0x100
	s_addc_u32 s50, s50, 0
	s_setprio 0
	s_barrier
	s_cmp_gt_u32 s51, 13
	s_cbranch_scc0 .LBB0_175
	s_and_b64 vcc, exec, s[10:11]
	s_cbranch_vccz .LBB0_178
	s_barrier

; #define PG8_STAGE(bufoff, gbase, voff) do { _Pragma("unroll") for (int _i = 0; _i < 2; ++_i) \
;         __builtin_amdgcn_global_load_lds((const unsigned*)((const char*)(gbase) + (voff)[_i]), (PG8_LAS unsigned*)(lds + (bufoff) + ldsw + _i * 8192), 16, 0, 0); } while (0)
; #define PG8_LDA(dst, b, h) do { _Pragma("unroll") for (int m = 0; m < 4; ++m) _Pragma("unroll") for (int k = 0; k < 2; ++k) dst[m][k] = *(const PG8_LAS bf16x8*)(lds + PG8_SA(b, h) + aoff + m * 2048 + k * 1024); } while (0)
; #define PG8_LDB(dst, b, h) do { _Pragma("unroll") for (int n = 0; n < 2; ++n) _Pragma("unroll") for (int k = 0; k < 2; ++k) dst[n][k] = *(const PG8_LAS bf16x8*)(lds + PG8_SB(b, h) + boff + n * 2048 + k * 1024); } while (0)
; #define PG8_MMA(ai, bj, At, Bt) do { __builtin_amdgcn_s_setprio(1); _Pragma("unroll") for (int m = 0; m < 4; ++m) _Pragma("unroll") for (int n = 0; n < 2; ++n) _Pragma("unroll") for (int k = 0; k < 2; ++k) \
;         acc[ai][bj][m][n] = __builtin_amdgcn_mfma_f32_16x16x32_bf16(Bt[n][k], At[m][k], acc[ai][bj][m][n], 0, 0, 0); __builtin_amdgcn_s_setprio(0); } while (0)
; #define PG8_WAIT_V(n) asm volatile("s_waitcnt vmcnt(" #n ")" ::: "memory")
; #define PG8_WAIT_L(n) asm volatile("s_waitcnt lgkmcnt(" #n ")" ::: "memory")
; template <class Epi, class Sched, bool ALIGN_EPI = false, bool SP2 = false, bool ABLK = false>
; __device__ __forceinline__ void gemm_phase(PG8_LAS unsigned char* lds, const Gemm g, const Sched& S, const Epi& E) {
;     ...
;             const bool last = (t == nt - 2);
;             const char* a1 = cA + (size_t)(t + 1) * kstepA;
;             const char* a2 = last ? nA : cA + (size_t)(t + 2) * kstepA; const char* b2 = last ? nB : cB + (size_t)(t + 2) * kstep;
;             const char* a3 = a2 + kstepA; const char* b3 = b2 + kstep;
;             if (last && has_next) S.a_ready(nxt);
;             if constexpr (SP2) {
;             PG8_LDB(B0, 0, 0); PG8_LDB(B1, 0, 1); PG8_SCHED; PG8_LDA(At, 0, 0); PG8_STAGE(PG8_SA(1, 1), a1 + hstepA, voffA);
;             PG8_WAIT_V(8); PG8_WAIT_L(0); PG8_BAR; PG8_MMA(0, 0, At, B0); PG8_MMA(0, 1, At, B1); PG8_BAR; PG8_SCHED;
;             PG8_LDA(At, 0, 1); PG8_STAGE(PG8_SB(0, 0), b2, voffB); PG8_STAGE(PG8_SB(0, 1), b2 + hstep, voffB); PG8_STAGE(PG8_SA(0, 0), a2, voffA);
;             PG8_WAIT_V(8); PG8_WAIT_L(0); PG8_BAR; PG8_MMA(1, 0, At, B0); PG8_MMA(1, 1, At, B1); PG8_BAR; PG8_SCHED;
.LBB0_256:
	ds_read_b128 v[144:147], v151
	ds_read_b128 v[156:159], v151 offset:1024
	ds_read_b128 v[160:163], v151 offset:2048
	ds_read_b128 v[168:171], v151 offset:3072
	ds_read_b128 v[172:175], v152
	ds_read_b128 v[176:179], v152 offset:1024
	ds_read_b128 v[180:183], v152 offset:2048
	ds_read_b128 v[184:187], v152 offset:3072
	s_add_u32 s16, s44, 0x4000
	s_addc_u32 s17, s45, 0
	s_cmp_eq_u32 s68, 40
	s_cselect_b32 s52, s0, s16
	s_cselect_b32 s53, s1, s17
	s_cselect_b32 s50, s36, s14
	s_cselect_b32 s51, s37, s15
	s_add_u32 s46, s52, 0x8000
	s_addc_u32 s47, s53, 0
	v_lshl_add_u64 v[164:165], s[44:45], 0, v[136:137]
	s_add_i32 m0, s7, 0xc000
	ds_read_b128 v[188:191], v153
	ds_read_b128 v[192:195], v153 offset:1024
	ds_read_b128 v[196:199], v153 offset:2048
	ds_read_b128 v[200:203], v153 offset:3072
	ds_read_b128 v[204:207], v153 offset:4096
	ds_read_b128 v[208:211], v153 offset:5120
	ds_read_b128 v[212:215], v153 offset:6144
	ds_read_b128 v[216:219], v153 offset:7168
	global_load_lds_dwordx4 v[164:165], off
	v_lshl_add_u64 v[164:165], s[44:45], 0, v[138:139]
	s_add_i32 m0, s7, 0xe000
	s_nop 0
	global_load_lds_dwordx4 v[164:165], off
	s_waitcnt vmcnt(8)
	s_waitcnt lgkmcnt(0)
	s_barrier
	s_setprio 1
	s_waitcnt lgkmcnt(0)
	v_mfma_f32_16x16x32_bf16 v[124:127], v[144:147], v[188:191], v[124:127]
	v_mfma_f32_16x16x32_bf16 v[120:123], v[160:163], v[188:191], v[120:123]
	v_mfma_f32_16x16x32_bf16 v[108:111], v[144:147], v[196:199], v[108:111]
	v_mfma_f32_16x16x32_bf16 v[104:107], v[160:163], v[196:199], v[104:107]
	v_mfma_f32_16x16x32_bf16 v[92:95], v[144:147], v[204:207], v[92:95]
	v_mfma_f32_16x16x32_bf16 v[88:91], v[160:163], v[204:207], v[88:91]
	v_mfma_f32_16x16x32_bf16 v[76:79], v[144:147], v[212:215], v[76:79]
	v_mfma_f32_16x16x32_bf16 v[72:75], v[160:163], v[212:215], v[72:75]
	v_mfma_f32_16x16x32_bf16 v[124:127], v[156:159], v[192:195], v[124:127]
	v_mfma_f32_16x16x32_bf16 v[120:123], v[168:171], v[192:195], v[120:123]
	v_mfma_f32_16x16x32_bf16 v[108:111], v[156:159], v[200:203], v[108:111]
	v_mfma_f32_16x16x32_bf16 v[104:107], v[168:171], v[200:203], v[104:107]
	v_mfma_f32_16x16x32_bf16 v[92:95], v[156:159], v[208:211], v[92:95]
	v_mfma_f32_16x16x32_bf16 v[88:91], v[168:171], v[208:211], v[88:91]
	v_mfma_f32_16x16x32_bf16 v[76:79], v[156:159], v[216:219], v[76:79]
	v_mfma_f32_16x16x32_bf16 v[72:75], v[168:171], v[216:219], v[72:75]
	s_setprio 0
	s_setprio 1
	v_mfma_f32_16x16x32_bf16 v[116:119], v[172:175], v[188:191], v[116:119]
	v_mfma_f32_16x16x32_bf16 v[112:115], v[180:183], v[188:191], v[112:115]
	v_mfma_f32_16x16x32_bf16 v[100:103], v[172:175], v[196:199], v[100:103]
	v_mfma_f32_16x16x32_bf16 v[96:99], v[180:183], v[196:199], v[96:99]
	v_mfma_f32_16x16x32_bf16 v[84:87], v[172:175], v[204:207], v[84:87]
	v_mfma_f32_16x16x32_bf16 v[80:83], v[180:183], v[204:207], v[80:83]
	v_mfma_f32_16x16x32_bf16 v[68:71], v[172:175], v[212:215], v[68:71]
	v_mfma_f32_16x16x32_bf16 v[64:67], v[180:183], v[212:215], v[64:67]
	v_mfma_f32_16x16x32_bf16 v[116:119], v[176:179], v[192:195], v[116:119]
	v_mfma_f32_16x16x32_bf16 v[112:115], v[184:187], v[192:195], v[112:115]
	v_mfma_f32_16x16x32_bf16 v[100:103], v[176:179], v[200:203], v[100:103]
	v_mfma_f32_16x16x32_bf16 v[96:99], v[184:187], v[200:203], v[96:99]
	v_mfma_f32_16x16x32_bf16 v[84:87], v[176:179], v[208:211], v[84:87]
	v_mfma_f32_16x16x32_bf16 v[80:83], v[184:187], v[208:211], v[80:83]
	v_mfma_f32_16x16x32_bf16 v[68:71], v[176:179], v[216:219], v[68:71]
	v_mfma_f32_16x16x32_bf16 v[64:67], v[184:187], v[216:219], v[64:67]
	s_setprio 0
	s_barrier
	s_add_i32 s16, s58, s4
	v_lshl_add_u64 v[164:165], s[50:51], 0, v[130:131]
	s_mov_b32 m0, s16
	ds_read_b128 v[188:191], v153 offset:16384
	ds_read_b128 v[192:195], v153 offset:17408
	ds_read_b128 v[196:199], v153 offset:18432
	ds_read_b128 v[200:203], v153 offset:19456
	ds_read_b128 v[204:207], v153 offset:20480
	ds_read_b128 v[208:211], v153 offset:21504
	ds_read_b128 v[212:215], v153 offset:22528
	ds_read_b128 v[216:219], v153 offset:23552
	global_load_lds_dwordx4 v[164:165], off
	s_add_i32 m0, s16, 0x2000
	s_add_u32 s16, s50, 0xb0000
	v_lshl_add_u64 v[220:221], s[50:51], 0, v[134:135]
	s_addc_u32 s17, s51, 0
	s_add_i32 s18, s59, s4
	global_load_lds_dwordx4 v[220:221], off
	v_lshl_add_u64 v[222:223], s[16:17], 0, v[130:131]
	s_mov_b32 m0, s18
	s_nop 0
	global_load_lds_dwordx4 v[222:223], off
	v_lshl_add_u64 v[222:223], s[16:17], 0, v[134:135]
	s_add_i32 m0, s18, 0x2000
	s_nop 0
	global_load_lds_dwordx4 v[222:223], off
	v_lshl_add_u64 v[222:223], s[52:53], 0, v[128:129]
	s_mov_b32 m0, s7
	s_nop 0
	global_load_lds_dwordx4 v[222:223], off
	v_lshl_add_u64 v[222:223], s[52:53], 0, v[132:133]
	s_mov_b32 m0, s54
	s_nop 0
	global_load_lds_dwordx4 v[222:223], off
	s_waitcnt vmcnt(8)
	s_waitcnt lgkmcnt(0)
	s_barrier
; #define PG8_STAGE(bufoff, gbase, voff) do { _Pragma("unroll") for (int _i = 0; _i < 2; ++_i) \
;         __builtin_amdgcn_global_load_lds((const unsigned*)((const char*)(gbase) + (voff)[_i]), (PG8_LAS unsigned*)(lds + (bufoff) + ldsw + _i * 8192), 16, 0, 0); } while (0)
; #define PG8_LDA(dst, b, h) do { _Pragma("unroll") for (int m = 0; m < 4; ++m) _Pragma("unroll") for (int k = 0; k < 2; ++k) dst[m][k] = *(const PG8_LAS bf16x8*)(lds + PG8_SA(b, h) + aoff + m * 2048 + k * 1024); } while (0)
; #define PG8_LDB(dst, b, h) do { _Pragma("unroll") for (int n = 0; n < 2; ++n) _Pragma("unroll") for (int k = 0; k < 2; ++k) dst[n][k] = *(const PG8_LAS bf16x8*)(lds + PG8_SB(b, h) + boff + n * 2048 + k * 1024); } while (0)
; #define PG8_MMA(ai, bj, At, Bt) do { __builtin_amdgcn_s_setprio(1); _Pragma("unroll") for (int m = 0; m < 4; ++m) _Pragma("unroll") for (int n = 0; n < 2; ++n) _Pragma("unroll") for (int k = 0; k < 2; ++k) \
;         acc[ai][bj][m][n] = __builtin_amdgcn_mfma_f32_16x16x32_bf16(Bt[n][k], At[m][k], acc[ai][bj][m][n], 0, 0, 0); __builtin_amdgcn_s_setprio(0); } while (0)
; #define PG8_WAIT_V(n) asm volatile("s_waitcnt vmcnt(" #n ")" ::: "memory")
; #define PG8_WAIT_L(n) asm volatile("s_waitcnt lgkmcnt(" #n ")" ::: "memory")
; #define PG8_BAR __builtin_amdgcn_s_barrier()
; #define PG8_SCHED __builtin_amdgcn_sched_barrier(0)
; template <class Epi, class Sched, bool ALIGN_EPI = false, bool SP2 = false, bool ABLK = false>
; __device__ __forceinline__ void gemm_phase(PG8_LAS unsigned char* lds, const Gemm g, const Sched& S, const Epi& E) {
;     ...
;             PG8_WAIT_V(8); PG8_WAIT_L(0); PG8_BAR; PG8_MMA(1, 0, At, B0); PG8_MMA(1, 1, At, B1); PG8_BAR; PG8_SCHED;
;             PG8_LDB(B0, 1, 0); PG8_LDB(B1, 1, 1); PG8_SCHED; PG8_LDA(At, 1, 0); PG8_STAGE(PG8_SA(0, 1), a2 + hstepA, voffA);
;             PG8_WAIT_V(8); PG8_WAIT_L(0); PG8_BAR; PG8_MMA(0, 0, At, B0); PG8_MMA(0, 1, At, B1); PG8_BAR; PG8_SCHED;
;             PG8_LDA(At, 1, 1); PG8_STAGE(PG8_SB(1, 0), b3, voffB); PG8_STAGE(PG8_SB(1, 1), b3 + hstep, voffB); PG8_STAGE(PG8_SA(1, 0), a3, voffA);
	s_setprio 1
	s_waitcnt lgkmcnt(0)
	v_mfma_f32_16x16x32_bf16 v[60:63], v[144:147], v[188:191], v[60:63]
	v_mfma_f32_16x16x32_bf16 v[56:59], v[160:163], v[188:191], v[56:59]
	v_mfma_f32_16x16x32_bf16 v[44:47], v[144:147], v[196:199], v[44:47]
	v_mfma_f32_16x16x32_bf16 v[40:43], v[160:163], v[196:199], v[40:43]
	v_mfma_f32_16x16x32_bf16 v[28:31], v[144:147], v[204:207], v[28:31]
	v_mfma_f32_16x16x32_bf16 v[24:27], v[160:163], v[204:207], v[24:27]
	v_mfma_f32_16x16x32_bf16 v[12:15], v[144:147], v[212:215], v[12:15]
	v_mfma_f32_16x16x32_bf16 v[8:11], v[160:163], v[212:215], v[8:11]
	v_mfma_f32_16x16x32_bf16 v[60:63], v[156:159], v[192:195], v[60:63]
	v_mfma_f32_16x16x32_bf16 v[56:59], v[168:171], v[192:195], v[56:59]
	v_mfma_f32_16x16x32_bf16 v[44:47], v[156:159], v[200:203], v[44:47]
	v_mfma_f32_16x16x32_bf16 v[40:43], v[168:171], v[200:203], v[40:43]
	v_mfma_f32_16x16x32_bf16 v[28:31], v[156:159], v[208:211], v[28:31]
	v_mfma_f32_16x16x32_bf16 v[24:27], v[168:171], v[208:211], v[24:27]
	v_mfma_f32_16x16x32_bf16 v[12:15], v[156:159], v[216:219], v[12:15]
	v_mfma_f32_16x16x32_bf16 v[8:11], v[168:171], v[216:219], v[8:11]
	s_setprio 0
	s_setprio 1
	v_mfma_f32_16x16x32_bf16 v[52:55], v[172:175], v[188:191], v[52:55]
	v_mfma_f32_16x16x32_bf16 v[48:51], v[180:183], v[188:191], v[48:51]
	v_mfma_f32_16x16x32_bf16 v[36:39], v[172:175], v[196:199], v[36:39]
	v_mfma_f32_16x16x32_bf16 v[32:35], v[180:183], v[196:199], v[32:35]
	v_mfma_f32_16x16x32_bf16 v[20:23], v[172:175], v[204:207], v[20:23]
	v_mfma_f32_16x16x32_bf16 v[16:19], v[180:183], v[204:207], v[16:19]
	v_mfma_f32_16x16x32_bf16 v[4:7], v[172:175], v[212:215], v[4:7]
	v_mfma_f32_16x16x32_bf16 v[0:3], v[180:183], v[212:215], v[0:3]
	v_mfma_f32_16x16x32_bf16 v[52:55], v[176:179], v[192:195], v[52:55]
	v_mfma_f32_16x16x32_bf16 v[48:51], v[184:187], v[192:195], v[48:51]
	v_mfma_f32_16x16x32_bf16 v[36:39], v[176:179], v[200:203], v[36:39]
	v_mfma_f32_16x16x32_bf16 v[32:35], v[184:187], v[200:203], v[32:35]
	v_mfma_f32_16x16x32_bf16 v[20:23], v[176:179], v[208:211], v[20:23]
	v_mfma_f32_16x16x32_bf16 v[16:19], v[184:187], v[208:211], v[16:19]
	v_mfma_f32_16x16x32_bf16 v[4:7], v[176:179], v[216:219], v[4:7]
	v_mfma_f32_16x16x32_bf16 v[0:3], v[184:187], v[216:219], v[0:3]
	s_setprio 0
	s_barrier
	s_add_i32 s18, 0, 0x18000
	v_add_u32_e32 v155, s18, v149
	s_add_i32 s19, 0, 0x1c000
	ds_read_b128 v[144:147], v155
	ds_read_b128 v[156:159], v155 offset:1024
	ds_read_b128 v[160:163], v155 offset:2048
	ds_read_b128 v[168:171], v155 offset:3072
	v_add_u32_e32 v155, s19, v149
	ds_read_b128 v[172:175], v155
	ds_read_b128 v[176:179], v155 offset:1024
	ds_read_b128 v[180:183], v155 offset:2048
	ds_read_b128 v[184:187], v155 offset:3072
	s_add_u32 s16, s52, 0x4000
	s_addc_u32 s17, s53, 0
	s_mov_b32 m0, s8
	v_lshl_add_u64 v[222:223], s[16:17], 0, v[128:129]
	ds_read_b128 v[188:191], v153 offset:32768
	ds_read_b128 v[192:195], v153 offset:33792
	ds_read_b128 v[196:199], v153 offset:34816
	ds_read_b128 v[200:203], v153 offset:35840
	ds_read_b128 v[204:207], v153 offset:36864
	ds_read_b128 v[208:211], v153 offset:37888
	ds_read_b128 v[212:215], v153 offset:38912
	ds_read_b128 v[216:219], v153 offset:39936
	global_load_lds_dwordx4 v[222:223], off
	v_lshl_add_u64 v[222:223], s[16:17], 0, v[132:133]
	s_mov_b32 m0, s9
	s_nop 0
	global_load_lds_dwordx4 v[222:223], off
	s_waitcnt vmcnt(8)
	s_waitcnt lgkmcnt(0)
	s_barrier
	s_setprio 1
	s_waitcnt lgkmcnt(0)
	v_mfma_f32_16x16x32_bf16 v[124:127], v[144:147], v[188:191], v[124:127]
	v_mfma_f32_16x16x32_bf16 v[120:123], v[160:163], v[188:191], v[120:123]
	v_mfma_f32_16x16x32_bf16 v[108:111], v[144:147], v[196:199], v[108:111]
	v_mfma_f32_16x16x32_bf16 v[104:107], v[160:163], v[196:199], v[104:107]
	v_mfma_f32_16x16x32_bf16 v[92:95], v[144:147], v[204:207], v[92:95]
	v_mfma_f32_16x16x32_bf16 v[88:91], v[160:163], v[204:207], v[88:91]
	v_mfma_f32_16x16x32_bf16 v[76:79], v[144:147], v[212:215], v[76:79]
	v_mfma_f32_16x16x32_bf16 v[72:75], v[160:163], v[212:215], v[72:75]
	v_mfma_f32_16x16x32_bf16 v[124:127], v[156:159], v[192:195], v[124:127]
	v_mfma_f32_16x16x32_bf16 v[120:123], v[168:171], v[192:195], v[120:123]
	v_mfma_f32_16x16x32_bf16 v[108:111], v[156:159], v[200:203], v[108:111]
	v_mfma_f32_16x16x32_bf16 v[104:107], v[168:171], v[200:203], v[104:107]
	v_mfma_f32_16x16x32_bf16 v[92:95], v[156:159], v[208:211], v[92:95]
	v_mfma_f32_16x16x32_bf16 v[88:91], v[168:171], v[208:211], v[88:91]
	v_mfma_f32_16x16x32_bf16 v[76:79], v[156:159], v[216:219], v[76:79]
	v_mfma_f32_16x16x32_bf16 v[72:75], v[168:171], v[216:219], v[72:75]
	s_setprio 0
	s_setprio 1
	v_mfma_f32_16x16x32_bf16 v[116:119], v[172:175], v[188:191], v[116:119]
	v_mfma_f32_16x16x32_bf16 v[112:115], v[180:183], v[188:191], v[112:115]
	v_mfma_f32_16x16x32_bf16 v[100:103], v[172:175], v[196:199], v[100:103]
	v_mfma_f32_16x16x32_bf16 v[96:99], v[180:183], v[196:199], v[96:99]
	v_mfma_f32_16x16x32_bf16 v[84:87], v[172:175], v[204:207], v[84:87]
	v_mfma_f32_16x16x32_bf16 v[80:83], v[180:183], v[204:207], v[80:83]
	v_mfma_f32_16x16x32_bf16 v[68:71], v[172:175], v[212:215], v[68:71]
	v_mfma_f32_16x16x32_bf16 v[64:67], v[180:183], v[212:215], v[64:67]
	v_mfma_f32_16x16x32_bf16 v[116:119], v[176:179], v[192:195], v[116:119]
	v_mfma_f32_16x16x32_bf16 v[112:115], v[184:187], v[192:195], v[112:115]
	v_mfma_f32_16x16x32_bf16 v[100:103], v[176:179], v[200:203], v[100:103]
	v_mfma_f32_16x16x32_bf16 v[96:99], v[184:187], v[200:203], v[96:99]
	v_mfma_f32_16x16x32_bf16 v[84:87], v[176:179], v[208:211], v[84:87]
	v_mfma_f32_16x16x32_bf16 v[80:83], v[184:187], v[208:211], v[80:83]
	v_mfma_f32_16x16x32_bf16 v[68:71], v[176:179], v[216:219], v[68:71]
	v_mfma_f32_16x16x32_bf16 v[64:67], v[184:187], v[216:219], v[64:67]
	s_setprio 0
	s_barrier
; #define PG8_STAGE(bufoff, gbase, voff) do { _Pragma("unroll") for (int _i = 0; _i < 2; ++_i) \
;         __builtin_amdgcn_global_load_lds((const unsigned*)((const char*)(gbase) + (voff)[_i]), (PG8_LAS unsigned*)(lds + (bufoff) + ldsw + _i * 8192), 16, 0, 0); } while (0)
; #define PG8_LDA(dst, b, h) do { _Pragma("unroll") for (int m = 0; m < 4; ++m) _Pragma("unroll") for (int k = 0; k < 2; ++k) dst[m][k] = *(const PG8_LAS bf16x8*)(lds + PG8_SA(b, h) + aoff + m * 2048 + k * 1024); } while (0)
; #define PG8_MMA(ai, bj, At, Bt) do { __builtin_amdgcn_s_setprio(1); _Pragma("unroll") for (int m = 0; m < 4; ++m) _Pragma("unroll") for (int n = 0; n < 2; ++n) _Pragma("unroll") for (int k = 0; k < 2; ++k) \
;         acc[ai][bj][m][n] = __builtin_amdgcn_mfma_f32_16x16x32_bf16(Bt[n][k], At[m][k], acc[ai][bj][m][n], 0, 0, 0); __builtin_amdgcn_s_setprio(0); } while (0)
; #define PG8_WAIT_V(n) asm volatile("s_waitcnt vmcnt(" #n ")" ::: "memory")
; #define PG8_WAIT_L(n) asm volatile("s_waitcnt lgkmcnt(" #n ")" ::: "memory")
; #define PG8_BAR __builtin_amdgcn_s_barrier()
; #define PG8_SCHED __builtin_amdgcn_sched_barrier(0)
; template <class Epi, class Sched, bool ALIGN_EPI = false, bool SP2 = false, bool ABLK = false>
; __device__ __forceinline__ void gemm_phase(PG8_LAS unsigned char* lds, const Gemm g, const Sched& S, const Epi& E) {
;     ...
;         for (int t = 0; t < nt; t += 2) {
;     ...
;             PG8_LDA(At, 1, 1); PG8_STAGE(PG8_SB(1, 0), b3, voffB); PG8_STAGE(PG8_SB(1, 1), b3 + hstep, voffB); PG8_STAGE(PG8_SA(1, 0), a3, voffA);
;             PG8_WAIT_V(8); PG8_WAIT_L(0); PG8_BAR; PG8_MMA(1, 0, At, B0); PG8_MMA(1, 1, At, B1); PG8_BAR; PG8_SCHED;
	s_add_i32 s16, s18, s4
	v_lshl_add_u64 v[164:165], v[164:165], 0, s[30:31]
	s_mov_b32 m0, s16
	ds_read_b128 v[188:191], v153 offset:49152
	ds_read_b128 v[192:195], v153 offset:50176
	ds_read_b128 v[196:199], v153 offset:51200
	ds_read_b128 v[200:203], v153 offset:52224
	ds_read_b128 v[204:207], v153 offset:53248
	ds_read_b128 v[208:211], v153 offset:54272
	ds_read_b128 v[212:215], v153 offset:55296
	ds_read_b128 v[216:219], v153 offset:56320
	global_load_lds_dwordx4 v[164:165], off
	s_add_i32 m0, s16, 0x2000
	s_add_u32 s16, s50, 0xb0080
	v_lshl_add_u64 v[164:165], v[220:221], 0, s[30:31]
	s_addc_u32 s17, s51, 0
	s_add_i32 s18, s19, s4
	global_load_lds_dwordx4 v[164:165], off
	v_lshl_add_u64 v[164:165], s[16:17], 0, v[130:131]
	s_mov_b32 m0, s18
	s_nop 0
	global_load_lds_dwordx4 v[164:165], off
	v_lshl_add_u64 v[164:165], s[16:17], 0, v[134:135]
	s_add_i32 m0, s18, 0x2000
	s_nop 0
	global_load_lds_dwordx4 v[164:165], off
	v_lshl_add_u64 v[164:165], s[46:47], 0, v[128:129]
	s_mov_b32 m0, s11
	s_nop 0
	global_load_lds_dwordx4 v[164:165], off
	v_lshl_add_u64 v[164:165], s[46:47], 0, v[132:133]
	s_mov_b32 m0, s55
	s_nop 0
	global_load_lds_dwordx4 v[164:165], off
	s_waitcnt vmcnt(8)
	s_waitcnt lgkmcnt(0)
	s_barrier
	s_setprio 1
	s_waitcnt lgkmcnt(0)
	v_mfma_f32_16x16x32_bf16 v[60:63], v[144:147], v[188:191], v[60:63]
	v_mfma_f32_16x16x32_bf16 v[56:59], v[160:163], v[188:191], v[56:59]
	v_mfma_f32_16x16x32_bf16 v[44:47], v[144:147], v[196:199], v[44:47]
	v_mfma_f32_16x16x32_bf16 v[40:43], v[160:163], v[196:199], v[40:43]
	v_mfma_f32_16x16x32_bf16 v[28:31], v[144:147], v[204:207], v[28:31]
	v_mfma_f32_16x16x32_bf16 v[24:27], v[160:163], v[204:207], v[24:27]
	v_mfma_f32_16x16x32_bf16 v[12:15], v[144:147], v[212:215], v[12:15]
	v_mfma_f32_16x16x32_bf16 v[8:11], v[160:163], v[212:215], v[8:11]
	v_mfma_f32_16x16x32_bf16 v[60:63], v[156:159], v[192:195], v[60:63]
	v_mfma_f32_16x16x32_bf16 v[56:59], v[168:171], v[192:195], v[56:59]
	v_mfma_f32_16x16x32_bf16 v[44:47], v[156:159], v[200:203], v[44:47]
	v_mfma_f32_16x16x32_bf16 v[40:43], v[168:171], v[200:203], v[40:43]
	v_mfma_f32_16x16x32_bf16 v[28:31], v[156:159], v[208:211], v[28:31]
	v_mfma_f32_16x16x32_bf16 v[24:27], v[168:171], v[208:211], v[24:27]
	v_mfma_f32_16x16x32_bf16 v[12:15], v[156:159], v[216:219], v[12:15]
	v_mfma_f32_16x16x32_bf16 v[8:11], v[168:171], v[216:219], v[8:11]
	s_setprio 0
	s_setprio 1
	v_mfma_f32_16x16x32_bf16 v[52:55], v[172:175], v[188:191], v[52:55]
	v_mfma_f32_16x16x32_bf16 v[48:51], v[180:183], v[188:191], v[48:51]
	v_mfma_f32_16x16x32_bf16 v[36:39], v[172:175], v[196:199], v[36:39]
	v_mfma_f32_16x16x32_bf16 v[32:35], v[180:183], v[196:199], v[32:35]
	v_mfma_f32_16x16x32_bf16 v[20:23], v[172:175], v[204:207], v[20:23]
	v_mfma_f32_16x16x32_bf16 v[16:19], v[180:183], v[204:207], v[16:19]
	v_mfma_f32_16x16x32_bf16 v[4:7], v[172:175], v[212:215], v[4:7]
	v_mfma_f32_16x16x32_bf16 v[0:3], v[180:183], v[212:215], v[0:3]
	v_mfma_f32_16x16x32_bf16 v[52:55], v[176:179], v[192:195], v[52:55]
	v_mfma_f32_16x16x32_bf16 v[48:51], v[184:187], v[192:195], v[48:51]
	v_mfma_f32_16x16x32_bf16 v[36:39], v[176:179], v[200:203], v[36:39]
	v_mfma_f32_16x16x32_bf16 v[32:35], v[184:187], v[200:203], v[32:35]
	v_mfma_f32_16x16x32_bf16 v[20:23], v[176:179], v[208:211], v[20:23]
	v_mfma_f32_16x16x32_bf16 v[16:19], v[184:187], v[208:211], v[16:19]
	v_mfma_f32_16x16x32_bf16 v[4:7], v[176:179], v[216:219], v[4:7]
	v_mfma_f32_16x16x32_bf16 v[0:3], v[184:187], v[216:219], v[0:3]
	s_add_i32 s68, s68, 2
	s_add_u32 s14, s14, 0x100
	s_addc_u32 s15, s15, 0
	s_add_u32 s44, s44, 0x10000
	s_addc_u32 s45, s45, 0
	s_setprio 0
	s_barrier
	s_cmp_gt_u32 s68, 41
	s_cbranch_scc0 .LBB0_256
	s_and_b64 vcc, exec, s[34:35]
	s_cbranch_vccz .LBB0_259
	s_barrier

; #define PG8_STAGE(bufoff, gbase, voff) do { _Pragma("unroll") for (int _i = 0; _i < 2; ++_i) \
;         __builtin_amdgcn_global_load_lds((const unsigned*)((const char*)(gbase) + (voff)[_i]), (PG8_LAS unsigned*)(lds + (bufoff) + ldsw + _i * 8192), 16, 0, 0); } while (0)
; #define PG8_LDA(dst, b, h) do { _Pragma("unroll") for (int m = 0; m < 4; ++m) _Pragma("unroll") for (int k = 0; k < 2; ++k) dst[m][k] = *(const PG8_LAS bf16x8*)(lds + PG8_SA(b, h) + aoff + m * 2048 + k * 1024); } while (0)
; #define PG8_LDB(dst, b, h) do { _Pragma("unroll") for (int n = 0; n < 2; ++n) _Pragma("unroll") for (int k = 0; k < 2; ++k) dst[n][k] = *(const PG8_LAS bf16x8*)(lds + PG8_SB(b, h) + boff + n * 2048 + k * 1024); } while (0)
; #define PG8_MMA(ai, bj, At, Bt) do { __builtin_amdgcn_s_setprio(1); _Pragma("unroll") for (int m = 0; m < 4; ++m) _Pragma("unroll") for (int n = 0; n < 2; ++n) _Pragma("unroll") for (int k = 0; k < 2; ++k) \
;         acc[ai][bj][m][n] = __builtin_amdgcn_mfma_f32_16x16x32_bf16(Bt[n][k], At[m][k], acc[ai][bj][m][n], 0, 0, 0); __builtin_amdgcn_s_setprio(0); } while (0)
; #define PG8_WAIT_V(n) asm volatile("s_waitcnt vmcnt(" #n ")" ::: "memory")
; #define PG8_WAIT_L(n) asm volatile("s_waitcnt lgkmcnt(" #n ")" ::: "memory")
; template <class Epi, class Sched, bool ALIGN_EPI = false, bool SP2 = false, bool ABLK = false>
; __device__ __forceinline__ void gemm_phase(PG8_LAS unsigned char* lds, const Gemm g, const Sched& S, const Epi& E) {
;     ...
;             const bool last = (t == nt - 2);
;             const char* a1 = cA + (size_t)(t + 1) * kstepA;
;             const char* a2 = last ? nA : cA + (size_t)(t + 2) * kstepA; const char* b2 = last ? nB : cB + (size_t)(t + 2) * kstep;
;             const char* a3 = a2 + kstepA; const char* b3 = b2 + kstep;
;             if (last && has_next) S.a_ready(nxt);
;             if constexpr (SP2) {
;             PG8_LDB(B0, 0, 0); PG8_LDB(B1, 0, 1); PG8_SCHED; PG8_LDA(At, 0, 0); PG8_STAGE(PG8_SA(1, 1), a1 + hstepA, voffA);
;             PG8_WAIT_V(8); PG8_WAIT_L(0); PG8_BAR; PG8_MMA(0, 0, At, B0); PG8_MMA(0, 1, At, B1); PG8_BAR; PG8_SCHED;
;             PG8_LDA(At, 0, 1); PG8_STAGE(PG8_SB(0, 0), b2, voffB); PG8_STAGE(PG8_SB(0, 1), b2 + hstep, voffB); PG8_STAGE(PG8_SA(0, 0), a2, voffA);
;             PG8_WAIT_V(8); PG8_WAIT_L(0); PG8_BAR; PG8_MMA(1, 0, At, B0); PG8_MMA(1, 1, At, B1); PG8_BAR; PG8_SCHED;
.LBB0_345:
	s_waitcnt lgkmcnt(0)
	ds_read_b128 v[152:155], v169
	ds_read_b128 v[156:159], v169 offset:1024
	ds_read_b128 v[160:163], v169 offset:2048
	ds_read_b128 v[176:179], v169 offset:3072
	ds_read_b128 v[180:183], v170
	ds_read_b128 v[184:187], v170 offset:1024
	ds_read_b128 v[188:191], v170 offset:2048
	ds_read_b128 v[192:195], v170 offset:3072
	s_add_u32 s10, s42, 0xfffc0080
	s_addc_u32 s11, s43, -1
	s_cmp_eq_u32 s9, 12
	s_cselect_b32 s67, s1, s11
	s_cselect_b32 s66, s4, s10
	s_cselect_b32 s53, s5, s8
	s_cselect_b32 s52, s6, s7
	v_lshl_add_u64 v[164:165], s[42:43], 0, v[144:145]
	s_add_i32 m0, s59, 0xc000
	ds_read_b128 v[196:199], v171
	ds_read_b128 v[200:203], v171 offset:1024
	ds_read_b128 v[204:207], v171 offset:2048
	ds_read_b128 v[208:211], v171 offset:3072
	ds_read_b128 v[212:215], v171 offset:4096
	ds_read_b128 v[216:219], v171 offset:5120
	ds_read_b128 v[220:223], v171 offset:6144
	ds_read_b128 v[224:227], v171 offset:7168
	global_load_lds_dwordx4 v[164:165], off
	v_lshl_add_u64 v[164:165], s[42:43], 0, v[146:147]
	s_add_i32 m0, s59, 0xe000
	s_nop 0
	global_load_lds_dwordx4 v[164:165], off
	s_waitcnt vmcnt(8)
	s_waitcnt lgkmcnt(0)
	s_barrier
	s_setprio 1
	s_waitcnt lgkmcnt(0)
	v_mfma_f32_16x16x32_bf16 v[124:127], v[152:155], v[196:199], v[124:127]
	v_mfma_f32_16x16x32_bf16 v[120:123], v[160:163], v[196:199], v[120:123]
	v_mfma_f32_16x16x32_bf16 v[108:111], v[152:155], v[204:207], v[108:111]
	v_mfma_f32_16x16x32_bf16 v[104:107], v[160:163], v[204:207], v[104:107]
	v_mfma_f32_16x16x32_bf16 v[92:95], v[152:155], v[212:215], v[92:95]
	v_mfma_f32_16x16x32_bf16 v[88:91], v[160:163], v[212:215], v[88:91]
	v_mfma_f32_16x16x32_bf16 v[76:79], v[152:155], v[220:223], v[76:79]
	v_mfma_f32_16x16x32_bf16 v[72:75], v[160:163], v[220:223], v[72:75]
	v_mfma_f32_16x16x32_bf16 v[124:127], v[156:159], v[200:203], v[124:127]
	v_mfma_f32_16x16x32_bf16 v[120:123], v[176:179], v[200:203], v[120:123]
	v_mfma_f32_16x16x32_bf16 v[108:111], v[156:159], v[208:211], v[108:111]
	v_mfma_f32_16x16x32_bf16 v[104:107], v[176:179], v[208:211], v[104:107]
	v_mfma_f32_16x16x32_bf16 v[92:95], v[156:159], v[216:219], v[92:95]
	v_mfma_f32_16x16x32_bf16 v[88:91], v[176:179], v[216:219], v[88:91]
	v_mfma_f32_16x16x32_bf16 v[76:79], v[156:159], v[224:227], v[76:79]
	v_mfma_f32_16x16x32_bf16 v[72:75], v[176:179], v[224:227], v[72:75]
	s_setprio 0
	s_setprio 1
	v_mfma_f32_16x16x32_bf16 v[116:119], v[180:183], v[196:199], v[116:119]
	v_mfma_f32_16x16x32_bf16 v[112:115], v[188:191], v[196:199], v[112:115]
	v_mfma_f32_16x16x32_bf16 v[100:103], v[180:183], v[204:207], v[100:103]
	v_mfma_f32_16x16x32_bf16 v[96:99], v[188:191], v[204:207], v[96:99]
	v_mfma_f32_16x16x32_bf16 v[84:87], v[180:183], v[212:215], v[84:87]
	v_mfma_f32_16x16x32_bf16 v[80:83], v[188:191], v[212:215], v[80:83]
	v_mfma_f32_16x16x32_bf16 v[68:71], v[180:183], v[220:223], v[68:71]
	v_mfma_f32_16x16x32_bf16 v[64:67], v[188:191], v[220:223], v[64:67]
	v_mfma_f32_16x16x32_bf16 v[116:119], v[184:187], v[200:203], v[116:119]
	v_mfma_f32_16x16x32_bf16 v[112:115], v[192:195], v[200:203], v[112:115]
	v_mfma_f32_16x16x32_bf16 v[100:103], v[184:187], v[208:211], v[100:103]
	v_mfma_f32_16x16x32_bf16 v[96:99], v[192:195], v[208:211], v[96:99]
	v_mfma_f32_16x16x32_bf16 v[84:87], v[184:187], v[216:219], v[84:87]
	v_mfma_f32_16x16x32_bf16 v[80:83], v[192:195], v[216:219], v[80:83]
	v_mfma_f32_16x16x32_bf16 v[68:71], v[184:187], v[224:227], v[68:71]
	v_mfma_f32_16x16x32_bf16 v[64:67], v[192:195], v[224:227], v[64:67]
	s_setprio 0
	s_barrier
	s_add_i32 s10, s34, s74
	v_lshl_add_u64 v[164:165], s[52:53], 0, v[130:131]
	s_mov_b32 m0, s10
	ds_read_b128 v[196:199], v171 offset:16384
	ds_read_b128 v[200:203], v171 offset:17408
	ds_read_b128 v[204:207], v171 offset:18432
	ds_read_b128 v[208:211], v171 offset:19456
	ds_read_b128 v[212:215], v171 offset:20480
	ds_read_b128 v[216:219], v171 offset:21504
	ds_read_b128 v[220:223], v171 offset:22528
	ds_read_b128 v[224:227], v171 offset:23552
	global_load_lds_dwordx4 v[164:165], off
	s_add_i32 m0, s10, 0x2000
	s_add_u32 s10, s52, 0x40000
	v_lshl_add_u64 v[228:229], s[52:53], 0, v[134:135]
	s_addc_u32 s11, s53, 0
	s_add_i32 s14, s35, s74
	global_load_lds_dwordx4 v[228:229], off
	v_lshl_add_u64 v[230:231], s[10:11], 0, v[130:131]
	s_mov_b32 m0, s14
	v_lshl_add_u64 v[232:233], s[66:67], 0, v[132:133]
	global_load_lds_dwordx4 v[230:231], off
	v_lshl_add_u64 v[230:231], s[10:11], 0, v[134:135]
	s_add_i32 m0, s14, 0x2000
	s_nop 0
	global_load_lds_dwordx4 v[230:231], off
	v_lshl_add_u64 v[230:231], s[66:67], 0, v[128:129]
	s_mov_b32 m0, s59
	s_nop 0
	global_load_lds_dwordx4 v[230:231], off
	s_mov_b32 m0, s75
	s_nop 0
	global_load_lds_dwordx4 v[232:233], off
	s_waitcnt vmcnt(8)
	s_waitcnt lgkmcnt(0)
	s_barrier
; #define PG8_STAGE(bufoff, gbase, voff) do { _Pragma("unroll") for (int _i = 0; _i < 2; ++_i) \
;         __builtin_amdgcn_global_load_lds((const unsigned*)((const char*)(gbase) + (voff)[_i]), (PG8_LAS unsigned*)(lds + (bufoff) + ldsw + _i * 8192), 16, 0, 0); } while (0)
; #define PG8_LDA(dst, b, h) do { _Pragma("unroll") for (int m = 0; m < 4; ++m) _Pragma("unroll") for (int k = 0; k < 2; ++k) dst[m][k] = *(const PG8_LAS bf16x8*)(lds + PG8_SA(b, h) + aoff + m * 2048 + k * 1024); } while (0)
; #define PG8_LDB(dst, b, h) do { _Pragma("unroll") for (int n = 0; n < 2; ++n) _Pragma("unroll") for (int k = 0; k < 2; ++k) dst[n][k] = *(const PG8_LAS bf16x8*)(lds + PG8_SB(b, h) + boff + n * 2048 + k * 1024); } while (0)
; #define PG8_MMA(ai, bj, At, Bt) do { __builtin_amdgcn_s_setprio(1); _Pragma("unroll") for (int m = 0; m < 4; ++m) _Pragma("unroll") for (int n = 0; n < 2; ++n) _Pragma("unroll") for (int k = 0; k < 2; ++k) \
;         acc[ai][bj][m][n] = __builtin_amdgcn_mfma_f32_16x16x32_bf16(Bt[n][k], At[m][k], acc[ai][bj][m][n], 0, 0, 0); __builtin_amdgcn_s_setprio(0); } while (0)
; #define PG8_WAIT_V(n) asm volatile("s_waitcnt vmcnt(" #n ")" ::: "memory")
; #define PG8_WAIT_L(n) asm volatile("s_waitcnt lgkmcnt(" #n ")" ::: "memory")
; #define PG8_BAR __builtin_amdgcn_s_barrier()
; #define PG8_SCHED __builtin_amdgcn_sched_barrier(0)
; template <class Epi, class Sched, bool ALIGN_EPI = false, bool SP2 = false, bool ABLK = false>
; __device__ __forceinline__ void gemm_phase(PG8_LAS unsigned char* lds, const Gemm g, const Sched& S, const Epi& E) {
;     ...
;             PG8_WAIT_V(8); PG8_WAIT_L(0); PG8_BAR; PG8_MMA(1, 0, At, B0); PG8_MMA(1, 1, At, B1); PG8_BAR; PG8_SCHED;
;             PG8_LDB(B0, 1, 0); PG8_LDB(B1, 1, 1); PG8_SCHED; PG8_LDA(At, 1, 0); PG8_STAGE(PG8_SA(0, 1), a2 + hstepA, voffA);
;             PG8_WAIT_V(8); PG8_WAIT_L(0); PG8_BAR; PG8_MMA(0, 0, At, B0); PG8_MMA(0, 1, At, B1); PG8_BAR; PG8_SCHED;
;             PG8_LDA(At, 1, 1); PG8_STAGE(PG8_SB(1, 0), b3, voffB); PG8_STAGE(PG8_SB(1, 1), b3 + hstep, voffB); PG8_STAGE(PG8_SA(1, 0), a3, voffA);
	s_setprio 1
	s_waitcnt lgkmcnt(0)
	v_mfma_f32_16x16x32_bf16 v[60:63], v[152:155], v[196:199], v[60:63]
	v_mfma_f32_16x16x32_bf16 v[56:59], v[160:163], v[196:199], v[56:59]
	v_mfma_f32_16x16x32_bf16 v[44:47], v[152:155], v[204:207], v[44:47]
	v_mfma_f32_16x16x32_bf16 v[40:43], v[160:163], v[204:207], v[40:43]
	v_mfma_f32_16x16x32_bf16 v[28:31], v[152:155], v[212:215], v[28:31]
	v_mfma_f32_16x16x32_bf16 v[24:27], v[160:163], v[212:215], v[24:27]
	v_mfma_f32_16x16x32_bf16 v[12:15], v[152:155], v[220:223], v[12:15]
	v_mfma_f32_16x16x32_bf16 v[8:11], v[160:163], v[220:223], v[8:11]
	v_mfma_f32_16x16x32_bf16 v[60:63], v[156:159], v[200:203], v[60:63]
	v_mfma_f32_16x16x32_bf16 v[56:59], v[176:179], v[200:203], v[56:59]
	v_mfma_f32_16x16x32_bf16 v[44:47], v[156:159], v[208:211], v[44:47]
	v_mfma_f32_16x16x32_bf16 v[40:43], v[176:179], v[208:211], v[40:43]
	v_mfma_f32_16x16x32_bf16 v[28:31], v[156:159], v[216:219], v[28:31]
	v_mfma_f32_16x16x32_bf16 v[24:27], v[176:179], v[216:219], v[24:27]
	v_mfma_f32_16x16x32_bf16 v[12:15], v[156:159], v[224:227], v[12:15]
	v_mfma_f32_16x16x32_bf16 v[8:11], v[176:179], v[224:227], v[8:11]
	s_setprio 0
	s_setprio 1
	v_mfma_f32_16x16x32_bf16 v[52:55], v[180:183], v[196:199], v[52:55]
	v_mfma_f32_16x16x32_bf16 v[48:51], v[188:191], v[196:199], v[48:51]
	v_mfma_f32_16x16x32_bf16 v[36:39], v[180:183], v[204:207], v[36:39]
	v_mfma_f32_16x16x32_bf16 v[32:35], v[188:191], v[204:207], v[32:35]
	v_mfma_f32_16x16x32_bf16 v[20:23], v[180:183], v[212:215], v[20:23]
	v_mfma_f32_16x16x32_bf16 v[16:19], v[188:191], v[212:215], v[16:19]
	v_mfma_f32_16x16x32_bf16 v[4:7], v[180:183], v[220:223], v[4:7]
	v_mfma_f32_16x16x32_bf16 v[0:3], v[188:191], v[220:223], v[0:3]
	v_mfma_f32_16x16x32_bf16 v[52:55], v[184:187], v[200:203], v[52:55]
	v_mfma_f32_16x16x32_bf16 v[48:51], v[192:195], v[200:203], v[48:51]
	v_mfma_f32_16x16x32_bf16 v[36:39], v[184:187], v[208:211], v[36:39]
	v_mfma_f32_16x16x32_bf16 v[32:35], v[192:195], v[208:211], v[32:35]
	v_mfma_f32_16x16x32_bf16 v[20:23], v[184:187], v[216:219], v[20:23]
	v_mfma_f32_16x16x32_bf16 v[16:19], v[192:195], v[216:219], v[16:19]
	v_mfma_f32_16x16x32_bf16 v[4:7], v[184:187], v[224:227], v[4:7]
	v_mfma_f32_16x16x32_bf16 v[0:3], v[192:195], v[224:227], v[0:3]
	s_setprio 0
	s_barrier
	s_add_i32 s14, 0, 0x18000
	v_add_u32_e32 v175, s14, v168
	s_add_i32 s15, 0, 0x1c000
	ds_read_b128 v[152:155], v175
	ds_read_b128 v[156:159], v175 offset:1024
	ds_read_b128 v[160:163], v175 offset:2048
	ds_read_b128 v[176:179], v175 offset:3072
	v_add_u32_e32 v175, s15, v168
	ds_read_b128 v[180:183], v175
	ds_read_b128 v[184:187], v175 offset:1024
	ds_read_b128 v[188:191], v175 offset:2048
	ds_read_b128 v[192:195], v175 offset:3072
	s_add_u32 s10, s66, 0x40000
	s_addc_u32 s11, s67, 0
	s_mov_b32 m0, s81
	v_lshl_add_u64 v[234:235], s[10:11], 0, v[128:129]
	ds_read_b128 v[196:199], v171 offset:32768
	ds_read_b128 v[200:203], v171 offset:33792
	ds_read_b128 v[204:207], v171 offset:34816
	ds_read_b128 v[208:211], v171 offset:35840
	ds_read_b128 v[212:215], v171 offset:36864
	ds_read_b128 v[216:219], v171 offset:37888
	ds_read_b128 v[220:223], v171 offset:38912
	ds_read_b128 v[224:227], v171 offset:39936
	global_load_lds_dwordx4 v[234:235], off
	v_lshl_add_u64 v[234:235], s[10:11], 0, v[132:133]
	s_mov_b32 m0, s12
	s_nop 0
	global_load_lds_dwordx4 v[234:235], off
	s_waitcnt vmcnt(8)
	s_waitcnt lgkmcnt(0)
	s_barrier
	s_setprio 1
	s_waitcnt lgkmcnt(0)
	v_mfma_f32_16x16x32_bf16 v[124:127], v[152:155], v[196:199], v[124:127]
	v_mfma_f32_16x16x32_bf16 v[120:123], v[160:163], v[196:199], v[120:123]
	v_mfma_f32_16x16x32_bf16 v[108:111], v[152:155], v[204:207], v[108:111]
	v_mfma_f32_16x16x32_bf16 v[104:107], v[160:163], v[204:207], v[104:107]
	v_mfma_f32_16x16x32_bf16 v[92:95], v[152:155], v[212:215], v[92:95]
	v_mfma_f32_16x16x32_bf16 v[88:91], v[160:163], v[212:215], v[88:91]
	v_mfma_f32_16x16x32_bf16 v[76:79], v[152:155], v[220:223], v[76:79]
	v_mfma_f32_16x16x32_bf16 v[72:75], v[160:163], v[220:223], v[72:75]
	v_mfma_f32_16x16x32_bf16 v[124:127], v[156:159], v[200:203], v[124:127]
	v_mfma_f32_16x16x32_bf16 v[120:123], v[176:179], v[200:203], v[120:123]
	v_mfma_f32_16x16x32_bf16 v[108:111], v[156:159], v[208:211], v[108:111]
	v_mfma_f32_16x16x32_bf16 v[104:107], v[176:179], v[208:211], v[104:107]
	v_mfma_f32_16x16x32_bf16 v[92:95], v[156:159], v[216:219], v[92:95]
	v_mfma_f32_16x16x32_bf16 v[88:91], v[176:179], v[216:219], v[88:91]
	v_mfma_f32_16x16x32_bf16 v[76:79], v[156:159], v[224:227], v[76:79]
	v_mfma_f32_16x16x32_bf16 v[72:75], v[176:179], v[224:227], v[72:75]
	s_setprio 0
	s_setprio 1
	v_mfma_f32_16x16x32_bf16 v[116:119], v[180:183], v[196:199], v[116:119]
	v_mfma_f32_16x16x32_bf16 v[112:115], v[188:191], v[196:199], v[112:115]
	v_mfma_f32_16x16x32_bf16 v[100:103], v[180:183], v[204:207], v[100:103]
	v_mfma_f32_16x16x32_bf16 v[96:99], v[188:191], v[204:207], v[96:99]
	v_mfma_f32_16x16x32_bf16 v[84:87], v[180:183], v[212:215], v[84:87]
	v_mfma_f32_16x16x32_bf16 v[80:83], v[188:191], v[212:215], v[80:83]
	v_mfma_f32_16x16x32_bf16 v[68:71], v[180:183], v[220:223], v[68:71]
	v_mfma_f32_16x16x32_bf16 v[64:67], v[188:191], v[220:223], v[64:67]
	v_mfma_f32_16x16x32_bf16 v[116:119], v[184:187], v[200:203], v[116:119]
	v_mfma_f32_16x16x32_bf16 v[112:115], v[192:195], v[200:203], v[112:115]
	v_mfma_f32_16x16x32_bf16 v[100:103], v[184:187], v[208:211], v[100:103]
	v_mfma_f32_16x16x32_bf16 v[96:99], v[192:195], v[208:211], v[96:99]
	v_mfma_f32_16x16x32_bf16 v[84:87], v[184:187], v[216:219], v[84:87]
	v_mfma_f32_16x16x32_bf16 v[80:83], v[192:195], v[216:219], v[80:83]
	v_mfma_f32_16x16x32_bf16 v[68:71], v[184:187], v[224:227], v[68:71]
	v_mfma_f32_16x16x32_bf16 v[64:67], v[192:195], v[224:227], v[64:67]
	s_setprio 0
	s_barrier
; #define PG8_STAGE(bufoff, gbase, voff) do { _Pragma("unroll") for (int _i = 0; _i < 2; ++_i) \
;         __builtin_amdgcn_global_load_lds((const unsigned*)((const char*)(gbase) + (voff)[_i]), (PG8_LAS unsigned*)(lds + (bufoff) + ldsw + _i * 8192), 16, 0, 0); } while (0)
; #define PG8_LDA(dst, b, h) do { _Pragma("unroll") for (int m = 0; m < 4; ++m) _Pragma("unroll") for (int k = 0; k < 2; ++k) dst[m][k] = *(const PG8_LAS bf16x8*)(lds + PG8_SA(b, h) + aoff + m * 2048 + k * 1024); } while (0)
; #define PG8_MMA(ai, bj, At, Bt) do { __builtin_amdgcn_s_setprio(1); _Pragma("unroll") for (int m = 0; m < 4; ++m) _Pragma("unroll") for (int n = 0; n < 2; ++n) _Pragma("unroll") for (int k = 0; k < 2; ++k) \
;         acc[ai][bj][m][n] = __builtin_amdgcn_mfma_f32_16x16x32_bf16(Bt[n][k], At[m][k], acc[ai][bj][m][n], 0, 0, 0); __builtin_amdgcn_s_setprio(0); } while (0)
; #define PG8_WAIT_V(n) asm volatile("s_waitcnt vmcnt(" #n ")" ::: "memory")
; #define PG8_WAIT_L(n) asm volatile("s_waitcnt lgkmcnt(" #n ")" ::: "memory")
; #define PG8_BAR __builtin_amdgcn_s_barrier()
; #define PG8_SCHED __builtin_amdgcn_sched_barrier(0)
; template <class Epi, class Sched, bool ALIGN_EPI = false, bool SP2 = false, bool ABLK = false>
; __device__ __forceinline__ void gemm_phase(PG8_LAS unsigned char* lds, const Gemm g, const Sched& S, const Epi& E) {
;     ...
;         for (int t = 0; t < nt; t += 2) {
;             const bool last = (t == nt - 2);
;     ...
;             PG8_LDA(At, 1, 1); PG8_STAGE(PG8_SB(1, 0), b3, voffB); PG8_STAGE(PG8_SB(1, 1), b3 + hstep, voffB); PG8_STAGE(PG8_SA(1, 0), a3, voffA);
;             PG8_WAIT_V(8); PG8_WAIT_L(0); PG8_BAR; PG8_MMA(1, 0, At, B0); PG8_MMA(1, 1, At, B1); PG8_BAR; PG8_SCHED;
	s_add_i32 s10, s14, s74
	v_lshl_add_u64 v[164:165], v[164:165], 0, s[28:29]
	s_mov_b32 m0, s10
	ds_read_b128 v[196:199], v171 offset:49152
	ds_read_b128 v[200:203], v171 offset:50176
	ds_read_b128 v[204:207], v171 offset:51200
	ds_read_b128 v[208:211], v171 offset:52224
	ds_read_b128 v[212:215], v171 offset:53248
	ds_read_b128 v[216:219], v171 offset:54272
	ds_read_b128 v[220:223], v171 offset:55296
	ds_read_b128 v[224:227], v171 offset:56320
	global_load_lds_dwordx4 v[164:165], off
	s_add_i32 m0, s10, 0x2000
	s_add_u32 s10, s52, 0x40080
	v_lshl_add_u64 v[164:165], v[228:229], 0, s[28:29]
	s_addc_u32 s11, s53, 0
	s_add_i32 s14, s15, s74
	global_load_lds_dwordx4 v[164:165], off
	v_lshl_add_u64 v[164:165], s[10:11], 0, v[130:131]
	s_mov_b32 m0, s14
	s_nop 0
	global_load_lds_dwordx4 v[164:165], off
	v_lshl_add_u64 v[164:165], s[10:11], 0, v[134:135]
	s_add_i32 m0, s14, 0x2000
	s_nop 0
	global_load_lds_dwordx4 v[164:165], off
	v_lshl_add_u64 v[164:165], v[230:231], 0, s[28:29]
	s_mov_b32 m0, s50
	s_nop 0
	global_load_lds_dwordx4 v[164:165], off
	v_lshl_add_u64 v[164:165], v[232:233], 0, s[28:29]
	s_mov_b32 m0, s51
	s_nop 0
	global_load_lds_dwordx4 v[164:165], off
	s_waitcnt vmcnt(8)
	s_waitcnt lgkmcnt(0)
	s_barrier
	s_setprio 1
	s_waitcnt lgkmcnt(0)
	v_mfma_f32_16x16x32_bf16 v[60:63], v[152:155], v[196:199], v[60:63]
	v_mfma_f32_16x16x32_bf16 v[56:59], v[160:163], v[196:199], v[56:59]
	v_mfma_f32_16x16x32_bf16 v[44:47], v[152:155], v[204:207], v[44:47]
	v_mfma_f32_16x16x32_bf16 v[40:43], v[160:163], v[204:207], v[40:43]
	v_mfma_f32_16x16x32_bf16 v[28:31], v[152:155], v[212:215], v[28:31]
	v_mfma_f32_16x16x32_bf16 v[24:27], v[160:163], v[212:215], v[24:27]
	v_mfma_f32_16x16x32_bf16 v[12:15], v[152:155], v[220:223], v[12:15]
	v_mfma_f32_16x16x32_bf16 v[8:11], v[160:163], v[220:223], v[8:11]
	v_mfma_f32_16x16x32_bf16 v[60:63], v[156:159], v[200:203], v[60:63]
	v_mfma_f32_16x16x32_bf16 v[56:59], v[176:179], v[200:203], v[56:59]
	v_mfma_f32_16x16x32_bf16 v[44:47], v[156:159], v[208:211], v[44:47]
	v_mfma_f32_16x16x32_bf16 v[40:43], v[176:179], v[208:211], v[40:43]
	v_mfma_f32_16x16x32_bf16 v[28:31], v[156:159], v[216:219], v[28:31]
	v_mfma_f32_16x16x32_bf16 v[24:27], v[176:179], v[216:219], v[24:27]
	v_mfma_f32_16x16x32_bf16 v[12:15], v[156:159], v[224:227], v[12:15]
	v_mfma_f32_16x16x32_bf16 v[8:11], v[176:179], v[224:227], v[8:11]
	s_setprio 0
	s_setprio 1
	v_mfma_f32_16x16x32_bf16 v[52:55], v[180:183], v[196:199], v[52:55]
	v_mfma_f32_16x16x32_bf16 v[48:51], v[188:191], v[196:199], v[48:51]
	v_mfma_f32_16x16x32_bf16 v[36:39], v[180:183], v[204:207], v[36:39]
	v_mfma_f32_16x16x32_bf16 v[32:35], v[188:191], v[204:207], v[32:35]
	v_mfma_f32_16x16x32_bf16 v[20:23], v[180:183], v[212:215], v[20:23]
	v_mfma_f32_16x16x32_bf16 v[16:19], v[188:191], v[212:215], v[16:19]
	v_mfma_f32_16x16x32_bf16 v[4:7], v[180:183], v[220:223], v[4:7]
	v_mfma_f32_16x16x32_bf16 v[0:3], v[188:191], v[220:223], v[0:3]
	v_mfma_f32_16x16x32_bf16 v[52:55], v[184:187], v[200:203], v[52:55]
	v_mfma_f32_16x16x32_bf16 v[48:51], v[192:195], v[200:203], v[48:51]
	v_mfma_f32_16x16x32_bf16 v[36:39], v[184:187], v[208:211], v[36:39]
	v_mfma_f32_16x16x32_bf16 v[32:35], v[192:195], v[208:211], v[32:35]
	v_mfma_f32_16x16x32_bf16 v[20:23], v[184:187], v[216:219], v[20:23]
	v_mfma_f32_16x16x32_bf16 v[16:19], v[192:195], v[216:219], v[16:19]
	v_mfma_f32_16x16x32_bf16 v[4:7], v[184:187], v[224:227], v[4:7]
	v_mfma_f32_16x16x32_bf16 v[0:3], v[192:195], v[224:227], v[0:3]
	s_add_i32 s9, s9, 2
	s_add_u32 s42, s42, 0x100
	s_addc_u32 s43, s43, 0
	s_add_u32 s7, s7, 0x100
	s_addc_u32 s8, s8, 0
	s_setprio 0
	s_barrier
	s_cmp_gt_u32 s9, 13
	s_cbranch_scc0 .LBB0_345
	s_and_b64 vcc, exec, s[30:31]
	s_cbranch_vccz .LBB0_348
	s_barrier

; #define PG8_STAGE(bufoff, gbase, voff) do { _Pragma("unroll") for (int _i = 0; _i < 2; ++_i) \
;         __builtin_amdgcn_global_load_lds((const unsigned*)((const char*)(gbase) + (voff)[_i]), (PG8_LAS unsigned*)(lds + (bufoff) + ldsw + _i * 8192), 16, 0, 0); } while (0)
; #define PG8_LDA(dst, b, h) do { _Pragma("unroll") for (int m = 0; m < 4; ++m) _Pragma("unroll") for (int k = 0; k < 2; ++k) dst[m][k] = *(const PG8_LAS bf16x8*)(lds + PG8_SA(b, h) + aoff + m * 2048 + k * 1024); } while (0)
; #define PG8_LDB(dst, b, h) do { _Pragma("unroll") for (int n = 0; n < 2; ++n) _Pragma("unroll") for (int k = 0; k < 2; ++k) dst[n][k] = *(const PG8_LAS bf16x8*)(lds + PG8_SB(b, h) + boff + n * 2048 + k * 1024); } while (0)
; #define PG8_MMA(ai, bj, At, Bt) do { __builtin_amdgcn_s_setprio(1); _Pragma("unroll") for (int m = 0; m < 4; ++m) _Pragma("unroll") for (int n = 0; n < 2; ++n) _Pragma("unroll") for (int k = 0; k < 2; ++k) \
;         acc[ai][bj][m][n] = __builtin_amdgcn_mfma_f32_16x16x32_bf16(Bt[n][k], At[m][k], acc[ai][bj][m][n], 0, 0, 0); __builtin_amdgcn_s_setprio(0); } while (0)
; #define PG8_WAIT_V(n) asm volatile("s_waitcnt vmcnt(" #n ")" ::: "memory")
; #define PG8_WAIT_L(n) asm volatile("s_waitcnt lgkmcnt(" #n ")" ::: "memory")
; template <class Epi, class Sched, bool ALIGN_EPI = false, bool SP2 = false, bool ABLK = false>
; __device__ __forceinline__ void gemm_phase(PG8_LAS unsigned char* lds, const Gemm g, const Sched& S, const Epi& E) {
;     ...
;             const bool last = (t == nt - 2);
;             const char* a1 = cA + (size_t)(t + 1) * kstepA;
;             const char* a2 = last ? nA : cA + (size_t)(t + 2) * kstepA; const char* b2 = last ? nB : cB + (size_t)(t + 2) * kstep;
;             const char* a3 = a2 + kstepA; const char* b3 = b2 + kstep;
;             if (last && has_next) S.a_ready(nxt);
;             if constexpr (SP2) {
;             PG8_LDB(B0, 0, 0); PG8_LDB(B1, 0, 1); PG8_SCHED; PG8_LDA(At, 0, 0); PG8_STAGE(PG8_SA(1, 1), a1 + hstepA, voffA);
;             PG8_WAIT_V(8); PG8_WAIT_L(0); PG8_BAR; PG8_MMA(0, 0, At, B0); PG8_MMA(0, 1, At, B1); PG8_BAR; PG8_SCHED;
;             PG8_LDA(At, 0, 1); PG8_STAGE(PG8_SB(0, 0), b2, voffB); PG8_STAGE(PG8_SB(0, 1), b2 + hstep, voffB); PG8_STAGE(PG8_SA(0, 0), a2, voffA);
;             PG8_WAIT_V(8); PG8_WAIT_L(0); PG8_BAR; PG8_MMA(1, 0, At, B0); PG8_MMA(1, 1, At, B1); PG8_BAR; PG8_SCHED;
.LBB0_824:
	ds_read_b128 v[156:159], v162
	ds_read_b128 v[168:171], v162 offset:1024
	ds_read_b128 v[172:175], v162 offset:2048
	ds_read_b128 v[176:179], v162 offset:3072
	ds_read_b128 v[180:183], v163
	ds_read_b128 v[184:187], v163 offset:1024
	ds_read_b128 v[188:191], v163 offset:2048
	ds_read_b128 v[192:195], v163 offset:3072
	s_add_u32 s11, s36, 0xfffc0080
	s_addc_u32 s14, s37, -1
	s_cmp_eq_u32 s10, 12
	s_cselect_b32 s53, s4, s14
	s_cselect_b32 s52, s5, s11
	s_cselect_b32 s51, s6, s9
	s_cselect_b32 s50, s7, s8
	v_lshl_add_u64 v[228:229], s[36:37], 0, v[148:149]
	s_add_i32 m0, s58, 0xc000
	ds_read_b128 v[196:199], v164
	ds_read_b128 v[200:203], v164 offset:1024
	ds_read_b128 v[204:207], v164 offset:2048
	ds_read_b128 v[208:211], v164 offset:3072
	ds_read_b128 v[212:215], v164 offset:4096
	ds_read_b128 v[216:219], v164 offset:5120
	ds_read_b128 v[220:223], v164 offset:6144
	ds_read_b128 v[224:227], v164 offset:7168
	global_load_lds_dwordx4 v[228:229], off
	v_lshl_add_u64 v[228:229], s[36:37], 0, v[150:151]
	s_add_i32 m0, s58, 0xe000
	s_nop 0
	global_load_lds_dwordx4 v[228:229], off
	s_waitcnt vmcnt(8)
	s_waitcnt lgkmcnt(0)
	s_barrier
	s_setprio 1
	s_waitcnt lgkmcnt(0)
	v_mfma_f32_16x16x32_bf16 v[124:127], v[156:159], v[196:199], v[124:127]
	v_mfma_f32_16x16x32_bf16 v[120:123], v[172:175], v[196:199], v[120:123]
	v_mfma_f32_16x16x32_bf16 v[108:111], v[156:159], v[204:207], v[108:111]
	v_mfma_f32_16x16x32_bf16 v[104:107], v[172:175], v[204:207], v[104:107]
	v_mfma_f32_16x16x32_bf16 v[92:95], v[156:159], v[212:215], v[92:95]
	v_mfma_f32_16x16x32_bf16 v[88:91], v[172:175], v[212:215], v[88:91]
	v_mfma_f32_16x16x32_bf16 v[76:79], v[156:159], v[220:223], v[76:79]
	v_mfma_f32_16x16x32_bf16 v[72:75], v[172:175], v[220:223], v[72:75]
	v_mfma_f32_16x16x32_bf16 v[124:127], v[168:171], v[200:203], v[124:127]
	v_mfma_f32_16x16x32_bf16 v[120:123], v[176:179], v[200:203], v[120:123]
	v_mfma_f32_16x16x32_bf16 v[108:111], v[168:171], v[208:211], v[108:111]
	v_mfma_f32_16x16x32_bf16 v[104:107], v[176:179], v[208:211], v[104:107]
	v_mfma_f32_16x16x32_bf16 v[92:95], v[168:171], v[216:219], v[92:95]
	v_mfma_f32_16x16x32_bf16 v[88:91], v[176:179], v[216:219], v[88:91]
	v_mfma_f32_16x16x32_bf16 v[76:79], v[168:171], v[224:227], v[76:79]
	v_mfma_f32_16x16x32_bf16 v[72:75], v[176:179], v[224:227], v[72:75]
	s_setprio 0
	s_setprio 1
	v_mfma_f32_16x16x32_bf16 v[116:119], v[180:183], v[196:199], v[116:119]
	v_mfma_f32_16x16x32_bf16 v[112:115], v[188:191], v[196:199], v[112:115]
	v_mfma_f32_16x16x32_bf16 v[100:103], v[180:183], v[204:207], v[100:103]
	v_mfma_f32_16x16x32_bf16 v[96:99], v[188:191], v[204:207], v[96:99]
	v_mfma_f32_16x16x32_bf16 v[84:87], v[180:183], v[212:215], v[84:87]
	v_mfma_f32_16x16x32_bf16 v[80:83], v[188:191], v[212:215], v[80:83]
	v_mfma_f32_16x16x32_bf16 v[68:71], v[180:183], v[220:223], v[68:71]
	v_mfma_f32_16x16x32_bf16 v[64:67], v[188:191], v[220:223], v[64:67]
	v_mfma_f32_16x16x32_bf16 v[116:119], v[184:187], v[200:203], v[116:119]
	v_mfma_f32_16x16x32_bf16 v[112:115], v[192:195], v[200:203], v[112:115]
	v_mfma_f32_16x16x32_bf16 v[100:103], v[184:187], v[208:211], v[100:103]
	v_mfma_f32_16x16x32_bf16 v[96:99], v[192:195], v[208:211], v[96:99]
	v_mfma_f32_16x16x32_bf16 v[84:87], v[184:187], v[216:219], v[84:87]
	v_mfma_f32_16x16x32_bf16 v[80:83], v[192:195], v[216:219], v[80:83]
	v_mfma_f32_16x16x32_bf16 v[68:71], v[184:187], v[224:227], v[68:71]
	v_mfma_f32_16x16x32_bf16 v[64:67], v[192:195], v[224:227], v[64:67]
	s_setprio 0
	s_barrier
	s_add_i32 s11, s70, s54
	v_lshl_add_u64 v[228:229], s[50:51], 0, v[132:133]
	s_mov_b32 m0, s11
	ds_read_b128 v[196:199], v164 offset:16384
	ds_read_b128 v[200:203], v164 offset:17408
	ds_read_b128 v[204:207], v164 offset:18432
	ds_read_b128 v[208:211], v164 offset:19456
	ds_read_b128 v[212:215], v164 offset:20480
	ds_read_b128 v[216:219], v164 offset:21504
	ds_read_b128 v[220:223], v164 offset:22528
	ds_read_b128 v[224:227], v164 offset:23552
	global_load_lds_dwordx4 v[228:229], off
	s_add_i32 m0, s11, 0x2000
	s_add_u32 s14, s50, 0x40000
	v_lshl_add_u64 v[230:231], s[50:51], 0, v[128:129]
	s_addc_u32 s15, s51, 0
	s_add_i32 s11, s71, s54
	global_load_lds_dwordx4 v[230:231], off
	v_lshl_add_u64 v[232:233], s[14:15], 0, v[132:133]
	s_mov_b32 m0, s11
	v_lshl_add_u64 v[234:235], s[52:53], 0, v[130:131]
	global_load_lds_dwordx4 v[232:233], off
	v_lshl_add_u64 v[232:233], s[14:15], 0, v[128:129]
	s_add_i32 m0, s11, 0x2000
	s_nop 0
	global_load_lds_dwordx4 v[232:233], off
	v_lshl_add_u64 v[232:233], s[52:53], 0, v[134:135]
	s_mov_b32 m0, s58
	s_nop 0
	global_load_lds_dwordx4 v[232:233], off
	s_mov_b32 m0, s59
	s_nop 0
	global_load_lds_dwordx4 v[234:235], off
	s_waitcnt vmcnt(8)
	s_waitcnt lgkmcnt(0)
	s_barrier
; #define PG8_STAGE(bufoff, gbase, voff) do { _Pragma("unroll") for (int _i = 0; _i < 2; ++_i) \
;         __builtin_amdgcn_global_load_lds((const unsigned*)((const char*)(gbase) + (voff)[_i]), (PG8_LAS unsigned*)(lds + (bufoff) + ldsw + _i * 8192), 16, 0, 0); } while (0)
; #define PG8_LDA(dst, b, h) do { _Pragma("unroll") for (int m = 0; m < 4; ++m) _Pragma("unroll") for (int k = 0; k < 2; ++k) dst[m][k] = *(const PG8_LAS bf16x8*)(lds + PG8_SA(b, h) + aoff + m * 2048 + k * 1024); } while (0)
; #define PG8_LDB(dst, b, h) do { _Pragma("unroll") for (int n = 0; n < 2; ++n) _Pragma("unroll") for (int k = 0; k < 2; ++k) dst[n][k] = *(const PG8_LAS bf16x8*)(lds + PG8_SB(b, h) + boff + n * 2048 + k * 1024); } while (0)
; #define PG8_MMA(ai, bj, At, Bt) do { __builtin_amdgcn_s_setprio(1); _Pragma("unroll") for (int m = 0; m < 4; ++m) _Pragma("unroll") for (int n = 0; n < 2; ++n) _Pragma("unroll") for (int k = 0; k < 2; ++k) \
;         acc[ai][bj][m][n] = __builtin_amdgcn_mfma_f32_16x16x32_bf16(Bt[n][k], At[m][k], acc[ai][bj][m][n], 0, 0, 0); __builtin_amdgcn_s_setprio(0); } while (0)
; #define PG8_WAIT_V(n) asm volatile("s_waitcnt vmcnt(" #n ")" ::: "memory")
; #define PG8_WAIT_L(n) asm volatile("s_waitcnt lgkmcnt(" #n ")" ::: "memory")
; #define PG8_BAR __builtin_amdgcn_s_barrier()
; #define PG8_SCHED __builtin_amdgcn_sched_barrier(0)
; template <class Epi, class Sched, bool ALIGN_EPI = false, bool SP2 = false, bool ABLK = false>
; __device__ __forceinline__ void gemm_phase(PG8_LAS unsigned char* lds, const Gemm g, const Sched& S, const Epi& E) {
;     ...
;             PG8_WAIT_V(8); PG8_WAIT_L(0); PG8_BAR; PG8_MMA(1, 0, At, B0); PG8_MMA(1, 1, At, B1); PG8_BAR; PG8_SCHED;
;             PG8_LDB(B0, 1, 0); PG8_LDB(B1, 1, 1); PG8_SCHED; PG8_LDA(At, 1, 0); PG8_STAGE(PG8_SA(0, 1), a2 + hstepA, voffA);
;             PG8_WAIT_V(8); PG8_WAIT_L(0); PG8_BAR; PG8_MMA(0, 0, At, B0); PG8_MMA(0, 1, At, B1); PG8_BAR; PG8_SCHED;
	s_setprio 1
	s_waitcnt lgkmcnt(0)
	v_mfma_f32_16x16x32_bf16 v[60:63], v[156:159], v[196:199], v[60:63]
	v_mfma_f32_16x16x32_bf16 v[56:59], v[172:175], v[196:199], v[56:59]
	v_mfma_f32_16x16x32_bf16 v[44:47], v[156:159], v[204:207], v[44:47]
	v_mfma_f32_16x16x32_bf16 v[40:43], v[172:175], v[204:207], v[40:43]
	v_mfma_f32_16x16x32_bf16 v[28:31], v[156:159], v[212:215], v[28:31]
	v_mfma_f32_16x16x32_bf16 v[24:27], v[172:175], v[212:215], v[24:27]
	v_mfma_f32_16x16x32_bf16 v[12:15], v[156:159], v[220:223], v[12:15]
	v_mfma_f32_16x16x32_bf16 v[8:11], v[172:175], v[220:223], v[8:11]
	v_mfma_f32_16x16x32_bf16 v[60:63], v[168:171], v[200:203], v[60:63]
	v_mfma_f32_16x16x32_bf16 v[56:59], v[176:179], v[200:203], v[56:59]
	v_mfma_f32_16x16x32_bf16 v[44:47], v[168:171], v[208:211], v[44:47]
	v_mfma_f32_16x16x32_bf16 v[40:43], v[176:179], v[208:211], v[40:43]
	v_mfma_f32_16x16x32_bf16 v[28:31], v[168:171], v[216:219], v[28:31]
	v_mfma_f32_16x16x32_bf16 v[24:27], v[176:179], v[216:219], v[24:27]
	v_mfma_f32_16x16x32_bf16 v[12:15], v[168:171], v[224:227], v[12:15]
	v_mfma_f32_16x16x32_bf16 v[8:11], v[176:179], v[224:227], v[8:11]
	s_setprio 0
	s_setprio 1
	v_mfma_f32_16x16x32_bf16 v[52:55], v[180:183], v[196:199], v[52:55]
	v_mfma_f32_16x16x32_bf16 v[48:51], v[188:191], v[196:199], v[48:51]
	v_mfma_f32_16x16x32_bf16 v[36:39], v[180:183], v[204:207], v[36:39]
	v_mfma_f32_16x16x32_bf16 v[32:35], v[188:191], v[204:207], v[32:35]
	v_mfma_f32_16x16x32_bf16 v[20:23], v[180:183], v[212:215], v[20:23]
	v_mfma_f32_16x16x32_bf16 v[16:19], v[188:191], v[212:215], v[16:19]
	v_mfma_f32_16x16x32_bf16 v[4:7], v[180:183], v[220:223], v[4:7]
	v_mfma_f32_16x16x32_bf16 v[0:3], v[188:191], v[220:223], v[0:3]
	v_mfma_f32_16x16x32_bf16 v[52:55], v[184:187], v[200:203], v[52:55]
	v_mfma_f32_16x16x32_bf16 v[48:51], v[192:195], v[200:203], v[48:51]
	v_mfma_f32_16x16x32_bf16 v[36:39], v[184:187], v[208:211], v[36:39]
	v_mfma_f32_16x16x32_bf16 v[32:35], v[192:195], v[208:211], v[32:35]
	v_mfma_f32_16x16x32_bf16 v[20:23], v[184:187], v[216:219], v[20:23]
	v_mfma_f32_16x16x32_bf16 v[16:19], v[192:195], v[216:219], v[16:19]
	v_mfma_f32_16x16x32_bf16 v[4:7], v[184:187], v[224:227], v[4:7]
	v_mfma_f32_16x16x32_bf16 v[0:3], v[192:195], v[224:227], v[0:3]
	s_setprio 0
	s_barrier
	s_add_i32 s11, 0, 0x18000
	s_add_i32 s16, 0, 0x1c000
	v_add_u32_e32 v176, s11, v161
	v_add_u32_e32 v192, s16, v161
	ds_read_b128 v[156:159], v176
	ds_read_b128 v[168:171], v176 offset:1024
	ds_read_b128 v[172:175], v176 offset:2048
	ds_read_b128 v[176:179], v176 offset:3072
	ds_read_b128 v[180:183], v192
	ds_read_b128 v[184:187], v192 offset:1024
	ds_read_b128 v[188:191], v192 offset:2048
	ds_read_b128 v[192:195], v192 offset:3072
	s_add_u32 s14, s52, 0x40000
	s_addc_u32 s15, s53, 0
	s_mov_b32 m0, s60
	v_lshl_add_u64 v[236:237], s[14:15], 0, v[134:135]
	ds_read_b128 v[196:199], v164 offset:32768
	ds_read_b128 v[200:203], v164 offset:33792
	ds_read_b128 v[204:207], v164 offset:34816
	ds_read_b128 v[208:211], v164 offset:35840
	ds_read_b128 v[212:215], v164 offset:36864
	ds_read_b128 v[216:219], v164 offset:37888
	ds_read_b128 v[220:223], v164 offset:38912
	ds_read_b128 v[224:227], v164 offset:39936
	global_load_lds_dwordx4 v[236:237], off
	v_lshl_add_u64 v[236:237], s[14:15], 0, v[130:131]
	s_mov_b32 m0, s61
	s_nop 0
	global_load_lds_dwordx4 v[236:237], off
	s_waitcnt vmcnt(8)
	s_waitcnt lgkmcnt(0)
	s_barrier
	s_setprio 1
	s_waitcnt lgkmcnt(0)
	v_mfma_f32_16x16x32_bf16 v[124:127], v[156:159], v[196:199], v[124:127]
	v_mfma_f32_16x16x32_bf16 v[120:123], v[172:175], v[196:199], v[120:123]
	v_mfma_f32_16x16x32_bf16 v[108:111], v[156:159], v[204:207], v[108:111]
	v_mfma_f32_16x16x32_bf16 v[104:107], v[172:175], v[204:207], v[104:107]
	v_mfma_f32_16x16x32_bf16 v[92:95], v[156:159], v[212:215], v[92:95]
	v_mfma_f32_16x16x32_bf16 v[88:91], v[172:175], v[212:215], v[88:91]
	v_mfma_f32_16x16x32_bf16 v[76:79], v[156:159], v[220:223], v[76:79]
	v_mfma_f32_16x16x32_bf16 v[72:75], v[172:175], v[220:223], v[72:75]
	v_mfma_f32_16x16x32_bf16 v[124:127], v[168:171], v[200:203], v[124:127]
	v_mfma_f32_16x16x32_bf16 v[120:123], v[176:179], v[200:203], v[120:123]
	v_mfma_f32_16x16x32_bf16 v[108:111], v[168:171], v[208:211], v[108:111]
	v_mfma_f32_16x16x32_bf16 v[104:107], v[176:179], v[208:211], v[104:107]
	v_mfma_f32_16x16x32_bf16 v[92:95], v[168:171], v[216:219], v[92:95]
	v_mfma_f32_16x16x32_bf16 v[88:91], v[176:179], v[216:219], v[88:91]
	v_mfma_f32_16x16x32_bf16 v[76:79], v[168:171], v[224:227], v[76:79]
	v_mfma_f32_16x16x32_bf16 v[72:75], v[176:179], v[224:227], v[72:75]
	s_setprio 0
	s_setprio 1
	v_mfma_f32_16x16x32_bf16 v[116:119], v[180:183], v[196:199], v[116:119]
	v_mfma_f32_16x16x32_bf16 v[112:115], v[188:191], v[196:199], v[112:115]
	v_mfma_f32_16x16x32_bf16 v[100:103], v[180:183], v[204:207], v[100:103]
	v_mfma_f32_16x16x32_bf16 v[96:99], v[188:191], v[204:207], v[96:99]
	v_mfma_f32_16x16x32_bf16 v[84:87], v[180:183], v[212:215], v[84:87]
	v_mfma_f32_16x16x32_bf16 v[80:83], v[188:191], v[212:215], v[80:83]
	v_mfma_f32_16x16x32_bf16 v[68:71], v[180:183], v[220:223], v[68:71]
	v_mfma_f32_16x16x32_bf16 v[64:67], v[188:191], v[220:223], v[64:67]
	v_mfma_f32_16x16x32_bf16 v[116:119], v[184:187], v[200:203], v[116:119]
	v_mfma_f32_16x16x32_bf16 v[112:115], v[192:195], v[200:203], v[112:115]
	v_mfma_f32_16x16x32_bf16 v[100:103], v[184:187], v[208:211], v[100:103]
	v_mfma_f32_16x16x32_bf16 v[96:99], v[192:195], v[208:211], v[96:99]
	v_mfma_f32_16x16x32_bf16 v[84:87], v[184:187], v[216:219], v[84:87]
	v_mfma_f32_16x16x32_bf16 v[80:83], v[192:195], v[216:219], v[80:83]
	v_mfma_f32_16x16x32_bf16 v[68:71], v[184:187], v[224:227], v[68:71]
	v_mfma_f32_16x16x32_bf16 v[64:67], v[192:195], v[224:227], v[64:67]
	s_setprio 0
	s_barrier
; #define PG8_STAGE(bufoff, gbase, voff) do { _Pragma("unroll") for (int _i = 0; _i < 2; ++_i) \
;         __builtin_amdgcn_global_load_lds((const unsigned*)((const char*)(gbase) + (voff)[_i]), (PG8_LAS unsigned*)(lds + (bufoff) + ldsw + _i * 8192), 16, 0, 0); } while (0)
; #define PG8_LDA(dst, b, h) do { _Pragma("unroll") for (int m = 0; m < 4; ++m) _Pragma("unroll") for (int k = 0; k < 2; ++k) dst[m][k] = *(const PG8_LAS bf16x8*)(lds + PG8_SA(b, h) + aoff + m * 2048 + k * 1024); } while (0)
; #define PG8_MMA(ai, bj, At, Bt) do { __builtin_amdgcn_s_setprio(1); _Pragma("unroll") for (int m = 0; m < 4; ++m) _Pragma("unroll") for (int n = 0; n < 2; ++n) _Pragma("unroll") for (int k = 0; k < 2; ++k) \
;         acc[ai][bj][m][n] = __builtin_amdgcn_mfma_f32_16x16x32_bf16(Bt[n][k], At[m][k], acc[ai][bj][m][n], 0, 0, 0); __builtin_amdgcn_s_setprio(0); } while (0)
; #define PG8_WAIT_V(n) asm volatile("s_waitcnt vmcnt(" #n ")" ::: "memory")
; #define PG8_WAIT_L(n) asm volatile("s_waitcnt lgkmcnt(" #n ")" ::: "memory")
; #define PG8_BAR __builtin_amdgcn_s_barrier()
; #define PG8_SCHED __builtin_amdgcn_sched_barrier(0)
; template <class Epi, class Sched, bool ALIGN_EPI = false, bool SP2 = false, bool ABLK = false>
; __device__ __forceinline__ void gemm_phase(PG8_LAS unsigned char* lds, const Gemm g, const Sched& S, const Epi& E) {
;     ...
;         for (int t = 0; t < nt; t += 2) {
;             const bool last = (t == nt - 2);
;     ...
;             PG8_LDA(At, 1, 1); PG8_STAGE(PG8_SB(1, 0), b3, voffB); PG8_STAGE(PG8_SB(1, 1), b3 + hstep, voffB); PG8_STAGE(PG8_SA(1, 0), a3, voffA);
;             PG8_WAIT_V(8); PG8_WAIT_L(0); PG8_BAR; PG8_MMA(1, 0, At, B0); PG8_MMA(1, 1, At, B1); PG8_BAR; PG8_SCHED;
	s_add_i32 s11, s11, s54
	v_lshl_add_u64 v[228:229], v[228:229], 0, s[30:31]
	s_mov_b32 m0, s11
	ds_read_b128 v[196:199], v164 offset:49152
	ds_read_b128 v[200:203], v164 offset:50176
	ds_read_b128 v[204:207], v164 offset:51200
	ds_read_b128 v[208:211], v164 offset:52224
	ds_read_b128 v[212:215], v164 offset:53248
	ds_read_b128 v[216:219], v164 offset:54272
	ds_read_b128 v[220:223], v164 offset:55296
	ds_read_b128 v[224:227], v164 offset:56320
	global_load_lds_dwordx4 v[228:229], off
	s_add_i32 m0, s11, 0x2000
	s_add_u32 s14, s50, 0x40080
	v_lshl_add_u64 v[228:229], v[230:231], 0, s[30:31]
	s_addc_u32 s15, s51, 0
	s_add_i32 s11, s16, s54
	global_load_lds_dwordx4 v[228:229], off
	v_lshl_add_u64 v[228:229], s[14:15], 0, v[132:133]
	s_mov_b32 m0, s11
	s_nop 0
	global_load_lds_dwordx4 v[228:229], off
	v_lshl_add_u64 v[228:229], s[14:15], 0, v[128:129]
	s_add_i32 m0, s11, 0x2000
	s_nop 0
	global_load_lds_dwordx4 v[228:229], off
	v_lshl_add_u64 v[228:229], v[232:233], 0, s[30:31]
	s_mov_b32 m0, s68
	s_nop 0
	global_load_lds_dwordx4 v[228:229], off
	v_lshl_add_u64 v[228:229], v[234:235], 0, s[30:31]
	s_mov_b32 m0, s69
	s_nop 0
	global_load_lds_dwordx4 v[228:229], off
	s_waitcnt vmcnt(8)
	s_waitcnt lgkmcnt(0)
	s_barrier
	s_setprio 1
	s_waitcnt lgkmcnt(0)
	v_mfma_f32_16x16x32_bf16 v[60:63], v[156:159], v[196:199], v[60:63]
	v_mfma_f32_16x16x32_bf16 v[56:59], v[172:175], v[196:199], v[56:59]
	v_mfma_f32_16x16x32_bf16 v[44:47], v[156:159], v[204:207], v[44:47]
	v_mfma_f32_16x16x32_bf16 v[40:43], v[172:175], v[204:207], v[40:43]
	v_mfma_f32_16x16x32_bf16 v[28:31], v[156:159], v[212:215], v[28:31]
	v_mfma_f32_16x16x32_bf16 v[24:27], v[172:175], v[212:215], v[24:27]
	v_mfma_f32_16x16x32_bf16 v[12:15], v[156:159], v[220:223], v[12:15]
	v_mfma_f32_16x16x32_bf16 v[8:11], v[172:175], v[220:223], v[8:11]
	v_mfma_f32_16x16x32_bf16 v[60:63], v[168:171], v[200:203], v[60:63]
	v_mfma_f32_16x16x32_bf16 v[56:59], v[176:179], v[200:203], v[56:59]
	v_mfma_f32_16x16x32_bf16 v[44:47], v[168:171], v[208:211], v[44:47]
	v_mfma_f32_16x16x32_bf16 v[40:43], v[176:179], v[208:211], v[40:43]
	v_mfma_f32_16x16x32_bf16 v[28:31], v[168:171], v[216:219], v[28:31]
	v_mfma_f32_16x16x32_bf16 v[24:27], v[176:179], v[216:219], v[24:27]
	v_mfma_f32_16x16x32_bf16 v[12:15], v[168:171], v[224:227], v[12:15]
	v_mfma_f32_16x16x32_bf16 v[8:11], v[176:179], v[224:227], v[8:11]
	s_setprio 0
	s_setprio 1
	v_mfma_f32_16x16x32_bf16 v[52:55], v[180:183], v[196:199], v[52:55]
	v_mfma_f32_16x16x32_bf16 v[48:51], v[188:191], v[196:199], v[48:51]
	v_mfma_f32_16x16x32_bf16 v[36:39], v[180:183], v[204:207], v[36:39]
	v_mfma_f32_16x16x32_bf16 v[32:35], v[188:191], v[204:207], v[32:35]
	v_mfma_f32_16x16x32_bf16 v[20:23], v[180:183], v[212:215], v[20:23]
	v_mfma_f32_16x16x32_bf16 v[16:19], v[188:191], v[212:215], v[16:19]
	v_mfma_f32_16x16x32_bf16 v[4:7], v[180:183], v[220:223], v[4:7]
	v_mfma_f32_16x16x32_bf16 v[0:3], v[188:191], v[220:223], v[0:3]
	v_mfma_f32_16x16x32_bf16 v[52:55], v[184:187], v[200:203], v[52:55]
	v_mfma_f32_16x16x32_bf16 v[48:51], v[192:195], v[200:203], v[48:51]
	v_mfma_f32_16x16x32_bf16 v[36:39], v[184:187], v[208:211], v[36:39]
	v_mfma_f32_16x16x32_bf16 v[32:35], v[192:195], v[208:211], v[32:35]
	v_mfma_f32_16x16x32_bf16 v[20:23], v[184:187], v[216:219], v[20:23]
	v_mfma_f32_16x16x32_bf16 v[16:19], v[192:195], v[216:219], v[16:19]
	v_mfma_f32_16x16x32_bf16 v[4:7], v[184:187], v[224:227], v[4:7]
	v_mfma_f32_16x16x32_bf16 v[0:3], v[192:195], v[224:227], v[0:3]
	s_add_i32 s10, s10, 2
	s_add_u32 s36, s36, 0x100
	s_addc_u32 s37, s37, 0
	s_add_u32 s8, s8, 0x100
	s_addc_u32 s9, s9, 0
	s_setprio 0
	s_barrier
	s_cmp_gt_u32 s10, 13
	s_cbranch_scc0 .LBB0_824
	s_and_b64 vcc, exec, s[34:35]
	s_cbranch_vccz .LBB0_827
	s_barrier

; #define PG8_STAGE(bufoff, gbase, voff) do { _Pragma("unroll") for (int _i = 0; _i < 2; ++_i) \
;         __builtin_amdgcn_global_load_lds((const unsigned*)((const char*)(gbase) + (voff)[_i]), (PG8_LAS unsigned*)(lds + (bufoff) + ldsw + _i * 8192), 16, 0, 0); } while (0)
; #define PG8_LDA(dst, b, h) do { _Pragma("unroll") for (int m = 0; m < 4; ++m) _Pragma("unroll") for (int k = 0; k < 2; ++k) dst[m][k] = *(const PG8_LAS bf16x8*)(lds + PG8_SA(b, h) + aoff + m * 2048 + k * 1024); } while (0)
; #define PG8_LDB(dst, b, h) do { _Pragma("unroll") for (int n = 0; n < 2; ++n) _Pragma("unroll") for (int k = 0; k < 2; ++k) dst[n][k] = *(const PG8_LAS bf16x8*)(lds + PG8_SB(b, h) + boff + n * 2048 + k * 1024); } while (0)
; #define PG8_MMA(ai, bj, At, Bt) do { __builtin_amdgcn_s_setprio(1); _Pragma("unroll") for (int m = 0; m < 4; ++m) _Pragma("unroll") for (int n = 0; n < 2; ++n) _Pragma("unroll") for (int k = 0; k < 2; ++k) \
;         acc[ai][bj][m][n] = __builtin_amdgcn_mfma_f32_16x16x32_bf16(Bt[n][k], At[m][k], acc[ai][bj][m][n], 0, 0, 0); __builtin_amdgcn_s_setprio(0); } while (0)
; #define PG8_WAIT_V(n) asm volatile("s_waitcnt vmcnt(" #n ")" ::: "memory")
; #define PG8_WAIT_L(n) asm volatile("s_waitcnt lgkmcnt(" #n ")" ::: "memory")
; template <class Epi, class Sched, bool ALIGN_EPI = false, bool SP2 = false, bool ABLK = false>
; __device__ __forceinline__ void gemm_phase(PG8_LAS unsigned char* lds, const Gemm g, const Sched& S, const Epi& E) {
;     ...
;             const bool last = (t == nt - 2);
;             const char* a1 = cA + (size_t)(t + 1) * kstepA;
;             const char* a2 = last ? nA : cA + (size_t)(t + 2) * kstepA; const char* b2 = last ? nB : cB + (size_t)(t + 2) * kstep;
;             const char* a3 = a2 + kstepA; const char* b3 = b2 + kstep;
;             if (last && has_next) S.a_ready(nxt);
;             if constexpr (SP2) {
;             PG8_LDB(B0, 0, 0); PG8_LDB(B1, 0, 1); PG8_SCHED; PG8_LDA(At, 0, 0); PG8_STAGE(PG8_SA(1, 1), a1 + hstepA, voffA);
;             PG8_WAIT_V(8); PG8_WAIT_L(0); PG8_BAR; PG8_MMA(0, 0, At, B0); PG8_MMA(0, 1, At, B1); PG8_BAR; PG8_SCHED;
;             PG8_LDA(At, 0, 1); PG8_STAGE(PG8_SB(0, 0), b2, voffB); PG8_STAGE(PG8_SB(0, 1), b2 + hstep, voffB); PG8_STAGE(PG8_SA(0, 0), a2, voffA);
;             PG8_WAIT_V(8); PG8_WAIT_L(0); PG8_BAR; PG8_MMA(1, 0, At, B0); PG8_MMA(1, 1, At, B1); PG8_BAR; PG8_SCHED;
.LBB0_905:
	ds_read_b128 v[144:147], v151
	ds_read_b128 v[156:159], v151 offset:1024
	ds_read_b128 v[160:163], v151 offset:2048
	ds_read_b128 v[168:171], v151 offset:3072
	ds_read_b128 v[172:175], v152
	ds_read_b128 v[176:179], v152 offset:1024
	ds_read_b128 v[180:183], v152 offset:2048
	ds_read_b128 v[184:187], v152 offset:3072
	s_add_u32 s16, s44, 0x4000
	s_addc_u32 s17, s45, 0
	s_cmp_eq_u32 s60, 40
	s_cselect_b32 s50, s0, s16
	s_cselect_b32 s51, s1, s17
	s_cselect_b32 s48, s42, s14
	s_cselect_b32 s49, s43, s15
	s_add_u32 s46, s50, 0x8000
	s_addc_u32 s47, s51, 0
	v_lshl_add_u64 v[164:165], s[44:45], 0, v[136:137]
	s_add_i32 m0, s7, 0xc000
	ds_read_b128 v[188:191], v153
	ds_read_b128 v[192:195], v153 offset:1024
	ds_read_b128 v[196:199], v153 offset:2048
	ds_read_b128 v[200:203], v153 offset:3072
	ds_read_b128 v[204:207], v153 offset:4096
	ds_read_b128 v[208:211], v153 offset:5120
	ds_read_b128 v[212:215], v153 offset:6144
	ds_read_b128 v[216:219], v153 offset:7168
	global_load_lds_dwordx4 v[164:165], off
	v_lshl_add_u64 v[164:165], s[44:45], 0, v[138:139]
	s_add_i32 m0, s7, 0xe000
	s_nop 0
	global_load_lds_dwordx4 v[164:165], off
	s_waitcnt vmcnt(8)
	s_waitcnt lgkmcnt(0)
	s_barrier
	s_setprio 1
	s_waitcnt lgkmcnt(0)
	v_mfma_f32_16x16x32_bf16 v[124:127], v[144:147], v[188:191], v[124:127]
	v_mfma_f32_16x16x32_bf16 v[120:123], v[160:163], v[188:191], v[120:123]
	v_mfma_f32_16x16x32_bf16 v[108:111], v[144:147], v[196:199], v[108:111]
	v_mfma_f32_16x16x32_bf16 v[104:107], v[160:163], v[196:199], v[104:107]
	v_mfma_f32_16x16x32_bf16 v[92:95], v[144:147], v[204:207], v[92:95]
	v_mfma_f32_16x16x32_bf16 v[88:91], v[160:163], v[204:207], v[88:91]
	v_mfma_f32_16x16x32_bf16 v[76:79], v[144:147], v[212:215], v[76:79]
	v_mfma_f32_16x16x32_bf16 v[72:75], v[160:163], v[212:215], v[72:75]
	v_mfma_f32_16x16x32_bf16 v[124:127], v[156:159], v[192:195], v[124:127]
	v_mfma_f32_16x16x32_bf16 v[120:123], v[168:171], v[192:195], v[120:123]
	v_mfma_f32_16x16x32_bf16 v[108:111], v[156:159], v[200:203], v[108:111]
	v_mfma_f32_16x16x32_bf16 v[104:107], v[168:171], v[200:203], v[104:107]
	v_mfma_f32_16x16x32_bf16 v[92:95], v[156:159], v[208:211], v[92:95]
	v_mfma_f32_16x16x32_bf16 v[88:91], v[168:171], v[208:211], v[88:91]
	v_mfma_f32_16x16x32_bf16 v[76:79], v[156:159], v[216:219], v[76:79]
	v_mfma_f32_16x16x32_bf16 v[72:75], v[168:171], v[216:219], v[72:75]
	s_setprio 0
	s_setprio 1
	v_mfma_f32_16x16x32_bf16 v[116:119], v[172:175], v[188:191], v[116:119]
	v_mfma_f32_16x16x32_bf16 v[112:115], v[180:183], v[188:191], v[112:115]
	v_mfma_f32_16x16x32_bf16 v[100:103], v[172:175], v[196:199], v[100:103]
	v_mfma_f32_16x16x32_bf16 v[96:99], v[180:183], v[196:199], v[96:99]
	v_mfma_f32_16x16x32_bf16 v[84:87], v[172:175], v[204:207], v[84:87]
	v_mfma_f32_16x16x32_bf16 v[80:83], v[180:183], v[204:207], v[80:83]
	v_mfma_f32_16x16x32_bf16 v[68:71], v[172:175], v[212:215], v[68:71]
	v_mfma_f32_16x16x32_bf16 v[64:67], v[180:183], v[212:215], v[64:67]
	v_mfma_f32_16x16x32_bf16 v[116:119], v[176:179], v[192:195], v[116:119]
	v_mfma_f32_16x16x32_bf16 v[112:115], v[184:187], v[192:195], v[112:115]
	v_mfma_f32_16x16x32_bf16 v[100:103], v[176:179], v[200:203], v[100:103]
	v_mfma_f32_16x16x32_bf16 v[96:99], v[184:187], v[200:203], v[96:99]
	v_mfma_f32_16x16x32_bf16 v[84:87], v[176:179], v[208:211], v[84:87]
	v_mfma_f32_16x16x32_bf16 v[80:83], v[184:187], v[208:211], v[80:83]
	v_mfma_f32_16x16x32_bf16 v[68:71], v[176:179], v[216:219], v[68:71]
	v_mfma_f32_16x16x32_bf16 v[64:67], v[184:187], v[216:219], v[64:67]
	s_setprio 0
	s_barrier
	s_add_i32 s16, s54, s4
	v_lshl_add_u64 v[164:165], s[48:49], 0, v[130:131]
	s_mov_b32 m0, s16
	ds_read_b128 v[188:191], v153 offset:16384
	ds_read_b128 v[192:195], v153 offset:17408
	ds_read_b128 v[196:199], v153 offset:18432
	ds_read_b128 v[200:203], v153 offset:19456
	ds_read_b128 v[204:207], v153 offset:20480
	ds_read_b128 v[208:211], v153 offset:21504
	ds_read_b128 v[212:215], v153 offset:22528
	ds_read_b128 v[216:219], v153 offset:23552
	global_load_lds_dwordx4 v[164:165], off
	s_add_i32 m0, s16, 0x2000
	s_add_u32 s16, s48, 0xb0000
	v_lshl_add_u64 v[220:221], s[48:49], 0, v[134:135]
	s_addc_u32 s17, s49, 0
	s_add_i32 s18, s55, s4
	global_load_lds_dwordx4 v[220:221], off
	v_lshl_add_u64 v[222:223], s[16:17], 0, v[130:131]
	s_mov_b32 m0, s18
	s_nop 0
	global_load_lds_dwordx4 v[222:223], off
	v_lshl_add_u64 v[222:223], s[16:17], 0, v[134:135]
	s_add_i32 m0, s18, 0x2000
	s_nop 0
	global_load_lds_dwordx4 v[222:223], off
	v_lshl_add_u64 v[222:223], s[50:51], 0, v[128:129]
	s_mov_b32 m0, s7
	s_nop 0
	global_load_lds_dwordx4 v[222:223], off
	v_lshl_add_u64 v[222:223], s[50:51], 0, v[132:133]
	s_mov_b32 m0, s8
	s_nop 0
	global_load_lds_dwordx4 v[222:223], off
	s_waitcnt vmcnt(8)
	s_waitcnt lgkmcnt(0)
	s_barrier
; #define PG8_STAGE(bufoff, gbase, voff) do { _Pragma("unroll") for (int _i = 0; _i < 2; ++_i) \
;         __builtin_amdgcn_global_load_lds((const unsigned*)((const char*)(gbase) + (voff)[_i]), (PG8_LAS unsigned*)(lds + (bufoff) + ldsw + _i * 8192), 16, 0, 0); } while (0)
; #define PG8_LDA(dst, b, h) do { _Pragma("unroll") for (int m = 0; m < 4; ++m) _Pragma("unroll") for (int k = 0; k < 2; ++k) dst[m][k] = *(const PG8_LAS bf16x8*)(lds + PG8_SA(b, h) + aoff + m * 2048 + k * 1024); } while (0)
; #define PG8_LDB(dst, b, h) do { _Pragma("unroll") for (int n = 0; n < 2; ++n) _Pragma("unroll") for (int k = 0; k < 2; ++k) dst[n][k] = *(const PG8_LAS bf16x8*)(lds + PG8_SB(b, h) + boff + n * 2048 + k * 1024); } while (0)
; #define PG8_MMA(ai, bj, At, Bt) do { __builtin_amdgcn_s_setprio(1); _Pragma("unroll") for (int m = 0; m < 4; ++m) _Pragma("unroll") for (int n = 0; n < 2; ++n) _Pragma("unroll") for (int k = 0; k < 2; ++k) \
;         acc[ai][bj][m][n] = __builtin_amdgcn_mfma_f32_16x16x32_bf16(Bt[n][k], At[m][k], acc[ai][bj][m][n], 0, 0, 0); __builtin_amdgcn_s_setprio(0); } while (0)
; #define PG8_WAIT_V(n) asm volatile("s_waitcnt vmcnt(" #n ")" ::: "memory")
; #define PG8_WAIT_L(n) asm volatile("s_waitcnt lgkmcnt(" #n ")" ::: "memory")
; #define PG8_BAR __builtin_amdgcn_s_barrier()
; #define PG8_SCHED __builtin_amdgcn_sched_barrier(0)
; template <class Epi, class Sched, bool ALIGN_EPI = false, bool SP2 = false, bool ABLK = false>
; __device__ __forceinline__ void gemm_phase(PG8_LAS unsigned char* lds, const Gemm g, const Sched& S, const Epi& E) {
;     ...
;             PG8_WAIT_V(8); PG8_WAIT_L(0); PG8_BAR; PG8_MMA(1, 0, At, B0); PG8_MMA(1, 1, At, B1); PG8_BAR; PG8_SCHED;
;             PG8_LDB(B0, 1, 0); PG8_LDB(B1, 1, 1); PG8_SCHED; PG8_LDA(At, 1, 0); PG8_STAGE(PG8_SA(0, 1), a2 + hstepA, voffA);
;             PG8_WAIT_V(8); PG8_WAIT_L(0); PG8_BAR; PG8_MMA(0, 0, At, B0); PG8_MMA(0, 1, At, B1); PG8_BAR; PG8_SCHED;
	s_setprio 1
	s_waitcnt lgkmcnt(0)
	v_mfma_f32_16x16x32_bf16 v[60:63], v[144:147], v[188:191], v[60:63]
	v_mfma_f32_16x16x32_bf16 v[56:59], v[160:163], v[188:191], v[56:59]
	v_mfma_f32_16x16x32_bf16 v[44:47], v[144:147], v[196:199], v[44:47]
	v_mfma_f32_16x16x32_bf16 v[40:43], v[160:163], v[196:199], v[40:43]
	v_mfma_f32_16x16x32_bf16 v[28:31], v[144:147], v[204:207], v[28:31]
	v_mfma_f32_16x16x32_bf16 v[24:27], v[160:163], v[204:207], v[24:27]
	v_mfma_f32_16x16x32_bf16 v[12:15], v[144:147], v[212:215], v[12:15]
	v_mfma_f32_16x16x32_bf16 v[8:11], v[160:163], v[212:215], v[8:11]
	v_mfma_f32_16x16x32_bf16 v[60:63], v[156:159], v[192:195], v[60:63]
	v_mfma_f32_16x16x32_bf16 v[56:59], v[168:171], v[192:195], v[56:59]
	v_mfma_f32_16x16x32_bf16 v[44:47], v[156:159], v[200:203], v[44:47]
	v_mfma_f32_16x16x32_bf16 v[40:43], v[168:171], v[200:203], v[40:43]
	v_mfma_f32_16x16x32_bf16 v[28:31], v[156:159], v[208:211], v[28:31]
	v_mfma_f32_16x16x32_bf16 v[24:27], v[168:171], v[208:211], v[24:27]
	v_mfma_f32_16x16x32_bf16 v[12:15], v[156:159], v[216:219], v[12:15]
	v_mfma_f32_16x16x32_bf16 v[8:11], v[168:171], v[216:219], v[8:11]
	s_setprio 0
	s_setprio 1
	v_mfma_f32_16x16x32_bf16 v[52:55], v[172:175], v[188:191], v[52:55]
	v_mfma_f32_16x16x32_bf16 v[48:51], v[180:183], v[188:191], v[48:51]
	v_mfma_f32_16x16x32_bf16 v[36:39], v[172:175], v[196:199], v[36:39]
	v_mfma_f32_16x16x32_bf16 v[32:35], v[180:183], v[196:199], v[32:35]
	v_mfma_f32_16x16x32_bf16 v[20:23], v[172:175], v[204:207], v[20:23]
	v_mfma_f32_16x16x32_bf16 v[16:19], v[180:183], v[204:207], v[16:19]
	v_mfma_f32_16x16x32_bf16 v[4:7], v[172:175], v[212:215], v[4:7]
	v_mfma_f32_16x16x32_bf16 v[0:3], v[180:183], v[212:215], v[0:3]
	v_mfma_f32_16x16x32_bf16 v[52:55], v[176:179], v[192:195], v[52:55]
	v_mfma_f32_16x16x32_bf16 v[48:51], v[184:187], v[192:195], v[48:51]
	v_mfma_f32_16x16x32_bf16 v[36:39], v[176:179], v[200:203], v[36:39]
	v_mfma_f32_16x16x32_bf16 v[32:35], v[184:187], v[200:203], v[32:35]
	v_mfma_f32_16x16x32_bf16 v[20:23], v[176:179], v[208:211], v[20:23]
	v_mfma_f32_16x16x32_bf16 v[16:19], v[184:187], v[208:211], v[16:19]
	v_mfma_f32_16x16x32_bf16 v[4:7], v[176:179], v[216:219], v[4:7]
	v_mfma_f32_16x16x32_bf16 v[0:3], v[184:187], v[216:219], v[0:3]
	s_setprio 0
	s_barrier
	s_add_i32 s18, 0, 0x18000
	v_add_u32_e32 v155, s18, v149
	s_add_i32 s19, 0, 0x1c000
	ds_read_b128 v[144:147], v155
	ds_read_b128 v[156:159], v155 offset:1024
	ds_read_b128 v[160:163], v155 offset:2048
	ds_read_b128 v[168:171], v155 offset:3072
	v_add_u32_e32 v155, s19, v149
	ds_read_b128 v[172:175], v155
	ds_read_b128 v[176:179], v155 offset:1024
	ds_read_b128 v[180:183], v155 offset:2048
	ds_read_b128 v[184:187], v155 offset:3072
	s_add_u32 s16, s50, 0x4000
	s_addc_u32 s17, s51, 0
	s_mov_b32 m0, s9
	v_lshl_add_u64 v[222:223], s[16:17], 0, v[128:129]
	ds_read_b128 v[188:191], v153 offset:32768
	ds_read_b128 v[192:195], v153 offset:33792
	ds_read_b128 v[196:199], v153 offset:34816
	ds_read_b128 v[200:203], v153 offset:35840
	ds_read_b128 v[204:207], v153 offset:36864
	ds_read_b128 v[208:211], v153 offset:37888
	ds_read_b128 v[212:215], v153 offset:38912
	ds_read_b128 v[216:219], v153 offset:39936
	global_load_lds_dwordx4 v[222:223], off
	v_lshl_add_u64 v[222:223], s[16:17], 0, v[132:133]
	s_mov_b32 m0, s10
	s_nop 0
	global_load_lds_dwordx4 v[222:223], off
	s_waitcnt vmcnt(8)
	s_waitcnt lgkmcnt(0)
	s_barrier
	s_setprio 1
	s_waitcnt lgkmcnt(0)
	v_mfma_f32_16x16x32_bf16 v[124:127], v[144:147], v[188:191], v[124:127]
	v_mfma_f32_16x16x32_bf16 v[120:123], v[160:163], v[188:191], v[120:123]
	v_mfma_f32_16x16x32_bf16 v[108:111], v[144:147], v[196:199], v[108:111]
	v_mfma_f32_16x16x32_bf16 v[104:107], v[160:163], v[196:199], v[104:107]
	v_mfma_f32_16x16x32_bf16 v[92:95], v[144:147], v[204:207], v[92:95]
	v_mfma_f32_16x16x32_bf16 v[88:91], v[160:163], v[204:207], v[88:91]
	v_mfma_f32_16x16x32_bf16 v[76:79], v[144:147], v[212:215], v[76:79]
	v_mfma_f32_16x16x32_bf16 v[72:75], v[160:163], v[212:215], v[72:75]
	v_mfma_f32_16x16x32_bf16 v[124:127], v[156:159], v[192:195], v[124:127]
	v_mfma_f32_16x16x32_bf16 v[120:123], v[168:171], v[192:195], v[120:123]
	v_mfma_f32_16x16x32_bf16 v[108:111], v[156:159], v[200:203], v[108:111]
	v_mfma_f32_16x16x32_bf16 v[104:107], v[168:171], v[200:203], v[104:107]
	v_mfma_f32_16x16x32_bf16 v[92:95], v[156:159], v[208:211], v[92:95]
	v_mfma_f32_16x16x32_bf16 v[88:91], v[168:171], v[208:211], v[88:91]
	v_mfma_f32_16x16x32_bf16 v[76:79], v[156:159], v[216:219], v[76:79]
	v_mfma_f32_16x16x32_bf16 v[72:75], v[168:171], v[216:219], v[72:75]
	s_setprio 0
	s_setprio 1
	v_mfma_f32_16x16x32_bf16 v[116:119], v[172:175], v[188:191], v[116:119]
	v_mfma_f32_16x16x32_bf16 v[112:115], v[180:183], v[188:191], v[112:115]
	v_mfma_f32_16x16x32_bf16 v[100:103], v[172:175], v[196:199], v[100:103]
	v_mfma_f32_16x16x32_bf16 v[96:99], v[180:183], v[196:199], v[96:99]
	v_mfma_f32_16x16x32_bf16 v[84:87], v[172:175], v[204:207], v[84:87]
	v_mfma_f32_16x16x32_bf16 v[80:83], v[180:183], v[204:207], v[80:83]
	v_mfma_f32_16x16x32_bf16 v[68:71], v[172:175], v[212:215], v[68:71]
	v_mfma_f32_16x16x32_bf16 v[64:67], v[180:183], v[212:215], v[64:67]
	v_mfma_f32_16x16x32_bf16 v[116:119], v[176:179], v[192:195], v[116:119]
	v_mfma_f32_16x16x32_bf16 v[112:115], v[184:187], v[192:195], v[112:115]
	v_mfma_f32_16x16x32_bf16 v[100:103], v[176:179], v[200:203], v[100:103]
	v_mfma_f32_16x16x32_bf16 v[96:99], v[184:187], v[200:203], v[96:99]
	v_mfma_f32_16x16x32_bf16 v[84:87], v[176:179], v[208:211], v[84:87]
	v_mfma_f32_16x16x32_bf16 v[80:83], v[184:187], v[208:211], v[80:83]
	v_mfma_f32_16x16x32_bf16 v[68:71], v[176:179], v[216:219], v[68:71]
	v_mfma_f32_16x16x32_bf16 v[64:67], v[184:187], v[216:219], v[64:67]
	s_setprio 0
	s_barrier
; #define PG8_STAGE(bufoff, gbase, voff) do { _Pragma("unroll") for (int _i = 0; _i < 2; ++_i) \
;         __builtin_amdgcn_global_load_lds((const unsigned*)((const char*)(gbase) + (voff)[_i]), (PG8_LAS unsigned*)(lds + (bufoff) + ldsw + _i * 8192), 16, 0, 0); } while (0)
; #define PG8_LDA(dst, b, h) do { _Pragma("unroll") for (int m = 0; m < 4; ++m) _Pragma("unroll") for (int k = 0; k < 2; ++k) dst[m][k] = *(const PG8_LAS bf16x8*)(lds + PG8_SA(b, h) + aoff + m * 2048 + k * 1024); } while (0)
; #define PG8_MMA(ai, bj, At, Bt) do { __builtin_amdgcn_s_setprio(1); _Pragma("unroll") for (int m = 0; m < 4; ++m) _Pragma("unroll") for (int n = 0; n < 2; ++n) _Pragma("unroll") for (int k = 0; k < 2; ++k) \
;         acc[ai][bj][m][n] = __builtin_amdgcn_mfma_f32_16x16x32_bf16(Bt[n][k], At[m][k], acc[ai][bj][m][n], 0, 0, 0); __builtin_amdgcn_s_setprio(0); } while (0)
; #define PG8_WAIT_V(n) asm volatile("s_waitcnt vmcnt(" #n ")" ::: "memory")
; #define PG8_WAIT_L(n) asm volatile("s_waitcnt lgkmcnt(" #n ")" ::: "memory")
; #define PG8_BAR __builtin_amdgcn_s_barrier()
; #define PG8_SCHED __builtin_amdgcn_sched_barrier(0)
; template <class Epi, class Sched, bool ALIGN_EPI = false, bool SP2 = false, bool ABLK = false>
; __device__ __forceinline__ void gemm_phase(PG8_LAS unsigned char* lds, const Gemm g, const Sched& S, const Epi& E) {
;     ...
;         for (int t = 0; t < nt; t += 2) {
;             const bool last = (t == nt - 2);
;     ...
;             PG8_LDA(At, 1, 1); PG8_STAGE(PG8_SB(1, 0), b3, voffB); PG8_STAGE(PG8_SB(1, 1), b3 + hstep, voffB); PG8_STAGE(PG8_SA(1, 0), a3, voffA);
;             PG8_WAIT_V(8); PG8_WAIT_L(0); PG8_BAR; PG8_MMA(1, 0, At, B0); PG8_MMA(1, 1, At, B1); PG8_BAR; PG8_SCHED;
	s_add_i32 s16, s18, s4
	v_lshl_add_u64 v[164:165], v[164:165], 0, s[30:31]
	s_mov_b32 m0, s16
	ds_read_b128 v[188:191], v153 offset:49152
	ds_read_b128 v[192:195], v153 offset:50176
	ds_read_b128 v[196:199], v153 offset:51200
	ds_read_b128 v[200:203], v153 offset:52224
	ds_read_b128 v[204:207], v153 offset:53248
	ds_read_b128 v[208:211], v153 offset:54272
	ds_read_b128 v[212:215], v153 offset:55296
	ds_read_b128 v[216:219], v153 offset:56320
	global_load_lds_dwordx4 v[164:165], off
	s_add_i32 m0, s16, 0x2000
	s_add_u32 s16, s48, 0xb0080
	v_lshl_add_u64 v[164:165], v[220:221], 0, s[30:31]
	s_addc_u32 s17, s49, 0
	s_add_i32 s18, s19, s4
	global_load_lds_dwordx4 v[164:165], off
	v_lshl_add_u64 v[164:165], s[16:17], 0, v[130:131]
	s_mov_b32 m0, s18
	s_nop 0
	global_load_lds_dwordx4 v[164:165], off
	v_lshl_add_u64 v[164:165], s[16:17], 0, v[134:135]
	s_add_i32 m0, s18, 0x2000
	s_nop 0
	global_load_lds_dwordx4 v[164:165], off
	v_lshl_add_u64 v[164:165], s[46:47], 0, v[128:129]
	s_mov_b32 m0, s52
	s_nop 0
	global_load_lds_dwordx4 v[164:165], off
	v_lshl_add_u64 v[164:165], s[46:47], 0, v[132:133]
	s_mov_b32 m0, s53
	s_nop 0
	global_load_lds_dwordx4 v[164:165], off
	s_waitcnt vmcnt(8)
	s_waitcnt lgkmcnt(0)
	s_barrier
	s_setprio 1
	s_waitcnt lgkmcnt(0)
	v_mfma_f32_16x16x32_bf16 v[60:63], v[144:147], v[188:191], v[60:63]
	v_mfma_f32_16x16x32_bf16 v[56:59], v[160:163], v[188:191], v[56:59]
	v_mfma_f32_16x16x32_bf16 v[44:47], v[144:147], v[196:199], v[44:47]
	v_mfma_f32_16x16x32_bf16 v[40:43], v[160:163], v[196:199], v[40:43]
	v_mfma_f32_16x16x32_bf16 v[28:31], v[144:147], v[204:207], v[28:31]
	v_mfma_f32_16x16x32_bf16 v[24:27], v[160:163], v[204:207], v[24:27]
	v_mfma_f32_16x16x32_bf16 v[12:15], v[144:147], v[212:215], v[12:15]
	v_mfma_f32_16x16x32_bf16 v[8:11], v[160:163], v[212:215], v[8:11]
	v_mfma_f32_16x16x32_bf16 v[60:63], v[156:159], v[192:195], v[60:63]
	v_mfma_f32_16x16x32_bf16 v[56:59], v[168:171], v[192:195], v[56:59]
	v_mfma_f32_16x16x32_bf16 v[44:47], v[156:159], v[200:203], v[44:47]
	v_mfma_f32_16x16x32_bf16 v[40:43], v[168:171], v[200:203], v[40:43]
	v_mfma_f32_16x16x32_bf16 v[28:31], v[156:159], v[208:211], v[28:31]
	v_mfma_f32_16x16x32_bf16 v[24:27], v[168:171], v[208:211], v[24:27]
	v_mfma_f32_16x16x32_bf16 v[12:15], v[156:159], v[216:219], v[12:15]
	v_mfma_f32_16x16x32_bf16 v[8:11], v[168:171], v[216:219], v[8:11]
	s_setprio 0
	s_setprio 1
	v_mfma_f32_16x16x32_bf16 v[52:55], v[172:175], v[188:191], v[52:55]
	v_mfma_f32_16x16x32_bf16 v[48:51], v[180:183], v[188:191], v[48:51]
	v_mfma_f32_16x16x32_bf16 v[36:39], v[172:175], v[196:199], v[36:39]
	v_mfma_f32_16x16x32_bf16 v[32:35], v[180:183], v[196:199], v[32:35]
	v_mfma_f32_16x16x32_bf16 v[20:23], v[172:175], v[204:207], v[20:23]
	v_mfma_f32_16x16x32_bf16 v[16:19], v[180:183], v[204:207], v[16:19]
	v_mfma_f32_16x16x32_bf16 v[4:7], v[172:175], v[212:215], v[4:7]
	v_mfma_f32_16x16x32_bf16 v[0:3], v[180:183], v[212:215], v[0:3]
	v_mfma_f32_16x16x32_bf16 v[52:55], v[176:179], v[192:195], v[52:55]
	v_mfma_f32_16x16x32_bf16 v[48:51], v[184:187], v[192:195], v[48:51]
	v_mfma_f32_16x16x32_bf16 v[36:39], v[176:179], v[200:203], v[36:39]
	v_mfma_f32_16x16x32_bf16 v[32:35], v[184:187], v[200:203], v[32:35]
	v_mfma_f32_16x16x32_bf16 v[20:23], v[176:179], v[208:211], v[20:23]
	v_mfma_f32_16x16x32_bf16 v[16:19], v[184:187], v[208:211], v[16:19]
	v_mfma_f32_16x16x32_bf16 v[4:7], v[176:179], v[216:219], v[4:7]
	v_mfma_f32_16x16x32_bf16 v[0:3], v[184:187], v[216:219], v[0:3]
	s_add_i32 s60, s60, 2
	s_add_u32 s14, s14, 0x100
	s_addc_u32 s15, s15, 0
	s_add_u32 s44, s44, 0x10000
	s_addc_u32 s45, s45, 0
	s_setprio 0
	s_barrier
	s_cmp_gt_u32 s60, 41
	s_cbranch_scc0 .LBB0_905
	s_and_b64 vcc, exec, s[34:35]
	s_cbranch_vccz .LBB0_908
	s_barrier
